# attention: validity bitmask + bfe/bfi masking, skip never-valid 16-key chunk, P.V accumulates in place (accumulator copy chains removed); GEMM accumulator clear with 64-bit moves
# speedup vs baseline: 1.0039x; 1.0030x over previous
; #define G_STAGE_A(bufoff, p0, p1, koff) do { \
;         __builtin_amdgcn_global_load_lds((const unsigned*)(gbase + (size_t)(unsigned)((p0) + (koff) + voffA[0])), (LAS unsigned*)(lds + (bufoff) + ldsw), 16, 0, 0); \
;         __builtin_amdgcn_global_load_lds((const unsigned*)(gbase + (size_t)(unsigned)((p1) + (koff) + voffA[1])), (LAS unsigned*)(lds + (bufoff) + ldsw + 8192), 16, 0, 0); } while (0)
; #define G_STAGE_B(bufoff, p, koff) do { \
;         __builtin_amdgcn_global_load_lds((const unsigned*)(gbase + (size_t)(unsigned)((p) + (koff) + voffB[0])), (LAS unsigned*)(lds + (bufoff) + ldsw), 16, 0, 0); \
;         __builtin_amdgcn_global_load_lds((const unsigned*)(gbase + (size_t)(unsigned)((p) + (koff) + voffB[1])), (LAS unsigned*)(lds + (bufoff) + ldsw + 8192), 16, 0, 0); } while (0)
; #define G_WAIT_V(n) asm volatile("s_waitcnt vmcnt(" #n ")" ::: "memory")
; #define G_BAR __builtin_amdgcn_s_barrier()
; template <class Epi>
; DI void gemm_phase(LAS unsigned char* lds, const Sched& S, const Epi& E, const int K) {
;     ...
;     f32x4 acc[2][2][4][2];
; #pragma unroll
;     for (int a = 0; a < 2; ++a)
; #pragma unroll
;         for (int b = 0; b < 2; ++b)
; #pragma unroll
;             for (int m = 0; m < 4; ++m)
; #pragma unroll
;                 for (int n = 0; n < 2; ++n) acc[a][b][m][n] = (f32x4){0.f, 0.f, 0.f, 0.f};
;     bf16x8 At[4][2], B0[2][2], B1[2][2];
;     ...
;     G_STAGE_B(G_SB(0, 0), cur.b, 0u); G_STAGE_B(G_SB(0, 1), cur.b + hstepB, 0u); G_STAGE_A(G_SA(0, 0), cur.a0, cur.a1, 0u); G_STAGE_A(G_SA(0, 1), cur.a2, cur.a3, 0u);
;     if (wr == 1) G_BAR;
;     G_WAIT_V(2); G_BAR;
;     ...
;     G_STAGE_B(G_SB(0, 0), cur.b, 0u); G_STAGE_A(G_SA(0, 0), cur.a0, cur.a1, 0u); G_STAGE_B(G_SB(0, 1), cur.b + hstepB, 0u); G_STAGE_A(G_SA(0, 1), cur.a2, cur.a3, 0u);
;     if (wr == 1) G_BAR;
;     G_WAIT_V(4); G_BAR;
;     ...
;     G_STAGE_B(G_SB(1, 0), cur.b, kstepB); G_STAGE_A(G_SA(1, 0), cur.a0, cur.a1, kstepA); G_STAGE_B(G_SB(1, 1), cur.b + hstepB, kstepB);
;     G_WAIT_V(6); G_BAR;
.LBB0_87:
	s_waitcnt lgkmcnt(0)
	s_add_u32 s18, s8, s56
	s_addc_u32 s19, s9, s39
	v_and_b32_e32 v160, 15, v1
	v_lshrrev_b32_e32 v10, 1, v1
	s_add_u32 s20, s10, s57
	v_and_b32_e32 v10, 24, v10
	v_lshlrev_b32_e32 v11, 6, v160
	v_readlane_b32 s1, v254, 62
	v_lshlrev_b32_e32 v1, 2, v1
	s_addc_u32 s21, s11, s38
	v_lshl_or_b32 v11, v10, 1, v11
	s_lshl_b32 s1, s1, 13
	v_and_b32_e32 v1, 32, v1
	s_lshl_b32 s0, s0, 5
	v_bitop3_b32 v12, v11, s1, v1 bitop3:0xde
	s_and_b32 s1, s0, 0x60
	s_lshl_b32 s0, s1, 7
	v_bitop3_b32 v207, v11, s0, v1 bitop3:0xde
	s_add_i32 s0, s60, 0x80
	v_add_u32_e32 v1, s0, v204
	s_add_i32 m0, s78, 0x18000
	s_waitcnt vmcnt(2)
	s_barrier
	global_load_lds_dwordx4 v1, s[82:83]
	v_add_u32_e32 v1, s0, v206
	s_add_i32 m0, s78, 0x1a000
	s_add_i32 s39, s78, 0x8000
	global_load_lds_dwordx4 v1, s[82:83]
	v_add_u32_e32 v1, 0x80, v9
	s_mov_b32 m0, s39
	s_add_i32 s38, s78, 0xa000
	global_load_lds_dwordx4 v1, s[82:83]
	v_add_u32_e32 v1, 0x80, v8
	s_mov_b32 m0, s38
	s_add_i32 s0, s60, 0x80080
	global_load_lds_dwordx4 v1, s[82:83]
	v_add_u32_e32 v1, s0, v204
	s_add_i32 m0, s78, 0x1c000
	v_mul_f32_e32 v0, 0x4f7ffffe, v0
	global_load_lds_dwordx4 v1, s[82:83]
	v_add_u32_e32 v1, s0, v206
	s_add_i32 m0, s78, 0x1e000
	s_cmpk_lt_u32 s12, 0x100
	global_load_lds_dwordx4 v1, s[82:83]
	s_cselect_b64 s[6:7], -1, 0
	s_add_u32 s80, s18, 0xb000
	s_addc_u32 s81, s19, 0
	s_add_u32 s70, s18, 0x16000
	s_addc_u32 s71, s19, 0
	s_add_u32 s24, s18, 0x5800
	s_addc_u32 s25, s19, 0
	s_add_u32 s72, s18, 0x10800
	v_cvt_u32_f32_e32 v0, v0
	v_writelane_b32 v254, s6, 63
	s_mov_b32 s0, 0
	s_addc_u32 s73, s19, 0
	v_writelane_b32 v255, s7, 0
	v_writelane_b32 v255, s0, 1
	s_add_u32 s66, s18, 0x1b800
	v_writelane_b32 v255, s18, 2
	s_addc_u32 s67, s19, 0
	s_add_u32 s68, s20, 0x5800
	v_writelane_b32 v255, s19, 3
	v_readfirstlane_b32 s18, v0
	v_and_b32_e32 v0, 1, v5
	v_writelane_b32 v255, s20, 4
	s_addc_u32 s69, s21, 0
	v_or_b32_e32 v211, s1, v10
	s_sub_i32 s1, 0, s35
	v_lshl_add_u32 v0, v0, 6, v7
	v_lshlrev_b32_e32 v1, 1, v6
	s_mul_i32 s1, s1, s18
	v_add3_u32 v212, v0, v1, s31
	v_and_b32_e32 v0, 1, v2
	s_waitcnt vmcnt(6)
	s_mul_hi_u32 s1, s18, s1
	v_lshl_add_u32 v0, v0, 6, v4
	v_lshlrev_b32_e32 v1, 1, v3
	v_writelane_b32 v255, s21, 5
	s_add_i32 s0, s18, s1
	v_add3_u32 v213, v0, v1, s31
	v_mov_b32_e32 v0, 0
	v_cmp_eq_u32_e64 s[6:7], 15, v160
	v_cmp_ne_u32_e64 s[8:9], 15, v160
	v_cmp_eq_u32_e64 s[10:11], 0, v160
	v_cmp_ne_u32_e64 s[12:13], 0, v160
	v_cmp_gt_u32_e64 s[14:15], 2, v160
	v_or_b32_e32 v208, 16, v160
	v_or_b32_e32 v209, 32, v160
	v_or_b32_e32 v210, 48, v160
	v_cmp_lt_u32_e64 s[16:17], 13, v160
	v_add_u32_e32 v184, -12, v160
	v_writelane_b32 v255, s0, 6
	v_add_u32_e32 v214, 0, v12
	v_mov_b32_e32 v1, v0
	v_mov_b64_e32 v[2:3], 0
	v_mov_b64_e32 v[4:5], 0
	v_mov_b64_e32 v[6:7], 0
	v_mov_b64_e32 v[8:9], 0
	v_mov_b64_e32 v[10:11], 0
	v_mov_b64_e32 v[12:13], 0
	v_mov_b64_e32 v[14:15], 0
	v_mov_b64_e32 v[16:17], 0
	v_mov_b64_e32 v[18:19], 0
	v_mov_b64_e32 v[20:21], 0
	v_mov_b64_e32 v[22:23], 0
	v_mov_b64_e32 v[24:25], 0
	v_mov_b64_e32 v[26:27], 0
	v_mov_b64_e32 v[28:29], 0
	v_mov_b64_e32 v[30:31], 0
	v_mov_b64_e32 v[32:33], 0
	v_mov_b64_e32 v[34:35], 0
	v_mov_b64_e32 v[36:37], 0
	v_mov_b64_e32 v[38:39], 0
	v_mov_b64_e32 v[40:41], 0
	v_mov_b64_e32 v[42:43], 0
	v_mov_b64_e32 v[44:45], 0
	v_mov_b64_e32 v[46:47], 0
	v_mov_b64_e32 v[48:49], 0
	v_mov_b64_e32 v[50:51], 0
	v_mov_b64_e32 v[52:53], 0
	v_mov_b64_e32 v[54:55], 0
	v_mov_b64_e32 v[56:57], 0
	v_mov_b64_e32 v[58:59], 0
	v_mov_b64_e32 v[60:61], 0
	v_mov_b64_e32 v[62:63], 0
	v_mov_b64_e32 v[64:65], 0
	v_mov_b64_e32 v[66:67], 0
	v_mov_b64_e32 v[68:69], 0
	v_mov_b64_e32 v[70:71], 0
	v_mov_b64_e32 v[72:73], 0
	v_mov_b64_e32 v[74:75], 0
	v_mov_b64_e32 v[76:77], 0
	v_mov_b64_e32 v[78:79], 0
	v_mov_b64_e32 v[80:81], 0
	v_mov_b64_e32 v[82:83], 0
	v_mov_b64_e32 v[84:85], 0
	v_mov_b64_e32 v[86:87], 0
	v_mov_b64_e32 v[88:89], 0
	v_mov_b64_e32 v[90:91], 0
	v_mov_b64_e32 v[92:93], 0
	v_mov_b64_e32 v[94:95], 0
	v_mov_b64_e32 v[96:97], 0
	v_mov_b64_e32 v[98:99], 0
	v_mov_b64_e32 v[100:101], 0
	v_mov_b64_e32 v[102:103], 0
	v_mov_b64_e32 v[104:105], 0
	v_mov_b64_e32 v[106:107], 0
	v_mov_b64_e32 v[108:109], 0
	v_mov_b64_e32 v[110:111], 0
	v_mov_b64_e32 v[112:113], 0
	v_mov_b64_e32 v[114:115], 0
	v_mov_b64_e32 v[116:117], 0
	v_mov_b64_e32 v[118:119], 0
	s_waitcnt vmcnt(0)
	v_mov_b64_e32 v[120:121], 0
	v_mov_b64_e32 v[122:123], 0
	v_mov_b64_e32 v[124:125], 0
	v_mov_b64_e32 v[126:127], 0
	s_barrier
	s_branch .LBB0_90
.LBB0_88:
	v_mov_b32_e32 v0, 0
	v_writelane_b32 v254, s59, 52
	s_mov_b32 s26, s89
	s_mov_b32 s60, s87
	s_mov_b32 s61, s94
	s_mov_b32 s27, s1
	s_mov_b32 s41, s86
	s_mov_b32 s58, s75
	v_writelane_b32 v255, s95, 1
	v_mov_b32_e32 v1, v0
	v_mov_b64_e32 v[2:3], 0
	v_mov_b64_e32 v[4:5], 0
	v_mov_b64_e32 v[6:7], 0
	v_mov_b64_e32 v[8:9], 0
	v_mov_b64_e32 v[10:11], 0
	v_mov_b64_e32 v[12:13], 0
	v_mov_b64_e32 v[14:15], 0
	v_mov_b64_e32 v[16:17], 0
	v_mov_b64_e32 v[18:19], 0
	v_mov_b64_e32 v[20:21], 0
	v_mov_b64_e32 v[22:23], 0
	v_mov_b64_e32 v[24:25], 0
	v_mov_b64_e32 v[26:27], 0
	v_mov_b64_e32 v[28:29], 0
	v_mov_b64_e32 v[30:31], 0
	v_mov_b64_e32 v[32:33], 0
	v_mov_b64_e32 v[34:35], 0
	v_mov_b64_e32 v[36:37], 0
	v_mov_b64_e32 v[38:39], 0
	v_mov_b64_e32 v[40:41], 0
	v_mov_b64_e32 v[42:43], 0
	v_mov_b64_e32 v[44:45], 0
	v_mov_b64_e32 v[46:47], 0
	v_mov_b64_e32 v[48:49], 0
	v_mov_b64_e32 v[50:51], 0
	v_mov_b64_e32 v[52:53], 0
	v_mov_b64_e32 v[54:55], 0
	v_mov_b64_e32 v[56:57], 0
	v_mov_b64_e32 v[58:59], 0
	v_mov_b64_e32 v[60:61], 0
	v_mov_b64_e32 v[62:63], 0
	v_mov_b64_e32 v[64:65], 0
	v_mov_b64_e32 v[66:67], 0
	v_mov_b64_e32 v[68:69], 0
	v_mov_b64_e32 v[70:71], 0
	v_mov_b64_e32 v[72:73], 0
	v_mov_b64_e32 v[74:75], 0
	v_mov_b64_e32 v[76:77], 0
	v_mov_b64_e32 v[78:79], 0
	v_mov_b64_e32 v[80:81], 0
	v_mov_b64_e32 v[82:83], 0
	v_mov_b64_e32 v[84:85], 0
	v_mov_b64_e32 v[86:87], 0
	v_mov_b64_e32 v[88:89], 0
	v_mov_b64_e32 v[90:91], 0
	v_mov_b64_e32 v[92:93], 0
	v_mov_b64_e32 v[94:95], 0
	v_mov_b64_e32 v[96:97], 0
	v_mov_b64_e32 v[98:99], 0
	v_mov_b64_e32 v[100:101], 0
	v_mov_b64_e32 v[102:103], 0
	v_mov_b64_e32 v[104:105], 0
	v_mov_b64_e32 v[106:107], 0
	v_mov_b64_e32 v[108:109], 0
	v_mov_b64_e32 v[110:111], 0
	v_mov_b64_e32 v[112:113], 0
	v_mov_b64_e32 v[114:115], 0
	v_mov_b64_e32 v[116:117], 0
	v_mov_b64_e32 v[118:119], 0
	v_mov_b64_e32 v[120:121], 0
	v_mov_b64_e32 v[122:123], 0
	v_mov_b64_e32 v[124:125], 0
	v_mov_b64_e32 v[126:127], 0

; #define G_STAGE_A(bufoff, p0, p1, koff) do { \
;         __builtin_amdgcn_global_load_lds((const unsigned*)(gbase + (size_t)(unsigned)((p0) + (koff) + voffA[0])), (LAS unsigned*)(lds + (bufoff) + ldsw), 16, 0, 0); \
;         __builtin_amdgcn_global_load_lds((const unsigned*)(gbase + (size_t)(unsigned)((p1) + (koff) + voffA[1])), (LAS unsigned*)(lds + (bufoff) + ldsw + 8192), 16, 0, 0); } while (0)
; #define G_STAGE_B(bufoff, p, koff) do { \
;         __builtin_amdgcn_global_load_lds((const unsigned*)(gbase + (size_t)(unsigned)((p) + (koff) + voffB[0])), (LAS unsigned*)(lds + (bufoff) + ldsw), 16, 0, 0); \
;         __builtin_amdgcn_global_load_lds((const unsigned*)(gbase + (size_t)(unsigned)((p) + (koff) + voffB[1])), (LAS unsigned*)(lds + (bufoff) + ldsw + 8192), 16, 0, 0); } while (0)
; #define G_WAIT_V(n) asm volatile("s_waitcnt vmcnt(" #n ")" ::: "memory")
; #define G_BAR __builtin_amdgcn_s_barrier()
; template <class Epi>
; DI void gemm_phase(LAS unsigned char* lds, const Sched& S, const Epi& E, const int K) {
;     ...
;     f32x4 acc[2][2][4][2];
; #pragma unroll
;     for (int a = 0; a < 2; ++a)
; #pragma unroll
;         for (int b = 0; b < 2; ++b)
; #pragma unroll
;             for (int m = 0; m < 4; ++m)
; #pragma unroll
;                 for (int n = 0; n < 2; ++n) acc[a][b][m][n] = (f32x4){0.f, 0.f, 0.f, 0.f};
;     bf16x8 At[4][2], B0[2][2], B1[2][2];
;     ...
;     G_STAGE_B(G_SB(0, 0), cur.b, 0u); G_STAGE_B(G_SB(0, 1), cur.b + hstepB, 0u); G_STAGE_A(G_SA(0, 0), cur.a0, cur.a1, 0u); G_STAGE_A(G_SA(0, 1), cur.a2, cur.a3, 0u);
;     if (wr == 1) G_BAR;
;     G_WAIT_V(2); G_BAR;
;     ...
;     G_STAGE_B(G_SB(0, 0), cur.b, 0u); G_STAGE_A(G_SA(0, 0), cur.a0, cur.a1, 0u); G_STAGE_B(G_SB(0, 1), cur.b + hstepB, 0u); G_STAGE_A(G_SA(0, 1), cur.a2, cur.a3, 0u);
;     if (wr == 1) G_BAR;
;     G_WAIT_V(4); G_BAR;
;     ...
;     G_STAGE_B(G_SB(1, 0), cur.b, kstepB); G_STAGE_A(G_SA(1, 0), cur.a0, cur.a1, kstepA); G_STAGE_B(G_SB(1, 1), cur.b + hstepB, kstepB);
;     G_WAIT_V(6); G_BAR;
.LBB0_186:
	v_lshrrev_b32_e32 v10, 1, v2
	v_and_b32_e32 v10, 24, v10
	v_and_b32_e32 v9, 15, v2
	v_lshlrev_b32_e32 v11, 1, v10
	v_lshlrev_b32_e32 v2, 2, v2
	s_lshl_b32 s7, s7, 5
	v_lshl_or_b32 v131, s9, 6, v9
	v_lshl_or_b32 v9, v9, 6, v11
	s_lshl_b32 s9, s9, 13
	v_and_b32_e32 v2, 32, v2
	s_and_b32 s7, s7, 0x60
	v_bitop3_b32 v11, v9, s9, v2 bitop3:0xde
	s_lshl_b32 s9, s7, 7
	v_bitop3_b32 v133, v9, s9, v2 bitop3:0xde
	s_add_i32 s9, s26, 0x80
	v_add_u32_e32 v2, s9, v128
	s_add_i32 m0, s25, 0x18000
	s_waitcnt vmcnt(2)
	s_barrier
	global_load_lds_dwordx4 v2, s[82:83]
	v_add_u32_e32 v2, s9, v130
	s_add_i32 m0, s25, 0x1a000
	s_add_i32 s45, s25, 0x8000
	global_load_lds_dwordx4 v2, s[82:83]
	v_add_u32_e32 v2, 0x80, v8
	s_mov_b32 m0, s45
	s_add_i32 s46, s25, 0xa000
	global_load_lds_dwordx4 v2, s[82:83]
	v_add_u32_e32 v2, 0x80, v7
	s_mov_b32 m0, s46
	s_addk_i32 s8, 0x80
	global_load_lds_dwordx4 v2, s[82:83]
	v_add_u32_e32 v2, s8, v128
	s_add_i32 m0, s25, 0x1c000
	v_mul_u32_u24_e32 v5, s17, v5
	global_load_lds_dwordx4 v2, s[82:83]
	v_add_u32_e32 v2, s8, v130
	s_add_i32 m0, s25, 0x1e000
	s_lshr_b32 s44, s18, 6
	global_load_lds_dwordx4 v2, s[82:83]
	v_and_b32_e32 v0, 1, v0
	v_mul_u32_u24_e32 v6, s17, v6
	s_waitcnt vmcnt(6)
	s_add_i32 s47, s44, -2
	v_and_b32_e32 v2, 1, v3
	v_lshl_add_u32 v0, v0, 6, v5
	v_lshlrev_b32_e32 v1, 1, v1
	s_cmpk_lt_u32 s6, 0x100
	v_lshl_add_u32 v2, v2, 6, v6
	v_lshlrev_b32_e32 v3, 1, v4
	v_add3_u32 v136, v0, v1, s31
	v_mov_b32_e32 v0, 0
	s_cselect_b64 s[12:13], -1, 0
	v_or_b32_e32 v134, s7, v10
	v_add3_u32 v135, v2, v3, s31
	s_mov_b32 s54, 0
	v_add_u32_e32 v137, 0, v11
	v_readlane_b32 s48, v253, 16
	v_readlane_b32 s50, v253, 17
	v_mov_b32_e32 v1, v0
	v_mov_b64_e32 v[2:3], 0
	v_mov_b64_e32 v[4:5], 0
	v_mov_b64_e32 v[6:7], 0
	v_mov_b64_e32 v[8:9], 0
	v_mov_b64_e32 v[10:11], 0
	v_mov_b64_e32 v[12:13], 0
	v_mov_b64_e32 v[14:15], 0
	v_mov_b64_e32 v[16:17], 0
	v_mov_b64_e32 v[18:19], 0
	v_mov_b64_e32 v[20:21], 0
	v_mov_b64_e32 v[22:23], 0
	v_mov_b64_e32 v[24:25], 0
	v_mov_b64_e32 v[26:27], 0
	v_mov_b64_e32 v[28:29], 0
	v_mov_b64_e32 v[30:31], 0
	v_mov_b64_e32 v[32:33], 0
	v_mov_b64_e32 v[34:35], 0
	v_mov_b64_e32 v[36:37], 0
	v_mov_b64_e32 v[38:39], 0
	v_mov_b64_e32 v[40:41], 0
	v_mov_b64_e32 v[42:43], 0
	v_mov_b64_e32 v[44:45], 0
	v_mov_b64_e32 v[46:47], 0
	v_mov_b64_e32 v[48:49], 0
	v_mov_b64_e32 v[50:51], 0
	v_mov_b64_e32 v[52:53], 0
	v_mov_b64_e32 v[54:55], 0
	v_mov_b64_e32 v[56:57], 0
	v_mov_b64_e32 v[58:59], 0
	v_mov_b64_e32 v[60:61], 0
	v_mov_b64_e32 v[62:63], 0
	v_mov_b64_e32 v[64:65], 0
	v_mov_b64_e32 v[66:67], 0
	v_mov_b64_e32 v[68:69], 0
	v_mov_b64_e32 v[70:71], 0
	v_mov_b64_e32 v[72:73], 0
	v_mov_b64_e32 v[74:75], 0
	v_mov_b64_e32 v[76:77], 0
	v_mov_b64_e32 v[78:79], 0
	v_mov_b64_e32 v[80:81], 0
	v_mov_b64_e32 v[82:83], 0
	v_mov_b64_e32 v[84:85], 0
	v_mov_b64_e32 v[86:87], 0
	v_mov_b64_e32 v[88:89], 0
	v_mov_b64_e32 v[90:91], 0
	v_mov_b64_e32 v[92:93], 0
	v_mov_b64_e32 v[94:95], 0
	v_mov_b64_e32 v[96:97], 0
	v_mov_b64_e32 v[98:99], 0
	v_mov_b64_e32 v[100:101], 0
	v_mov_b64_e32 v[102:103], 0
	v_mov_b64_e32 v[104:105], 0
	v_mov_b64_e32 v[106:107], 0
	v_mov_b64_e32 v[108:109], 0
	v_mov_b64_e32 v[110:111], 0
	v_mov_b64_e32 v[112:113], 0
	v_mov_b64_e32 v[114:115], 0
	v_mov_b64_e32 v[116:117], 0
	v_mov_b64_e32 v[118:119], 0
	v_mov_b64_e32 v[120:121], 0
	v_mov_b64_e32 v[122:123], 0
	v_mov_b64_e32 v[124:125], 0
	v_mov_b64_e32 v[126:127], 0
	s_barrier
	s_branch .LBB0_189
.LBB0_187:
	v_mov_b32_e32 v0, 0
	s_mov_b32 s48, s55
	s_mov_b32 s50, s56
	s_mov_b32 s26, s57
	s_mov_b32 s35, s58
	s_mov_b32 s36, s59
	s_mov_b32 s37, s60
	s_mov_b32 s27, s61
	s_mov_b32 s54, s66
	v_mov_b32_e32 v1, v0
	v_mov_b64_e32 v[2:3], 0
	v_mov_b64_e32 v[4:5], 0
	v_mov_b64_e32 v[6:7], 0
	v_mov_b64_e32 v[8:9], 0
	v_mov_b64_e32 v[10:11], 0
	v_mov_b64_e32 v[12:13], 0
	v_mov_b64_e32 v[14:15], 0
	v_mov_b64_e32 v[16:17], 0
	v_mov_b64_e32 v[18:19], 0
	v_mov_b64_e32 v[20:21], 0
	v_mov_b64_e32 v[22:23], 0
	v_mov_b64_e32 v[24:25], 0
	v_mov_b64_e32 v[26:27], 0
	v_mov_b64_e32 v[28:29], 0
	v_mov_b64_e32 v[30:31], 0
	v_mov_b64_e32 v[32:33], 0
	v_mov_b64_e32 v[34:35], 0
	v_mov_b64_e32 v[36:37], 0
	v_mov_b64_e32 v[38:39], 0
	v_mov_b64_e32 v[40:41], 0
	v_mov_b64_e32 v[42:43], 0
	v_mov_b64_e32 v[44:45], 0
	v_mov_b64_e32 v[46:47], 0
	v_mov_b64_e32 v[48:49], 0
	v_mov_b64_e32 v[50:51], 0
	v_mov_b64_e32 v[52:53], 0
	v_mov_b64_e32 v[54:55], 0
	v_mov_b64_e32 v[56:57], 0
	v_mov_b64_e32 v[58:59], 0
	v_mov_b64_e32 v[60:61], 0
	v_mov_b64_e32 v[62:63], 0
	v_mov_b64_e32 v[64:65], 0
	v_mov_b64_e32 v[66:67], 0
	v_mov_b64_e32 v[68:69], 0
	v_mov_b64_e32 v[70:71], 0
	v_mov_b64_e32 v[72:73], 0
	v_mov_b64_e32 v[74:75], 0
	v_mov_b64_e32 v[76:77], 0
	v_mov_b64_e32 v[78:79], 0
	v_mov_b64_e32 v[80:81], 0
	v_mov_b64_e32 v[82:83], 0
	v_mov_b64_e32 v[84:85], 0
	v_mov_b64_e32 v[86:87], 0
	v_mov_b64_e32 v[88:89], 0
	v_mov_b64_e32 v[90:91], 0
	v_mov_b64_e32 v[92:93], 0
	v_mov_b64_e32 v[94:95], 0
	v_mov_b64_e32 v[96:97], 0
	v_mov_b64_e32 v[98:99], 0
	v_mov_b64_e32 v[100:101], 0
	v_mov_b64_e32 v[102:103], 0
	v_mov_b64_e32 v[104:105], 0
	v_mov_b64_e32 v[106:107], 0
	v_mov_b64_e32 v[108:109], 0
	v_mov_b64_e32 v[110:111], 0
	v_mov_b64_e32 v[112:113], 0
	v_mov_b64_e32 v[114:115], 0
	v_mov_b64_e32 v[116:117], 0
	v_mov_b64_e32 v[118:119], 0
	v_mov_b64_e32 v[120:121], 0
	v_mov_b64_e32 v[122:123], 0
	v_mov_b64_e32 v[124:125], 0
	v_mov_b64_e32 v[126:127], 0

; #define G_STAGE_A(bufoff, p0, p1, koff) do { \
;         __builtin_amdgcn_global_load_lds((const unsigned*)(gbase + (size_t)(unsigned)((p0) + (koff) + voffA[0])), (LAS unsigned*)(lds + (bufoff) + ldsw), 16, 0, 0); \
;         __builtin_amdgcn_global_load_lds((const unsigned*)(gbase + (size_t)(unsigned)((p1) + (koff) + voffA[1])), (LAS unsigned*)(lds + (bufoff) + ldsw + 8192), 16, 0, 0); } while (0)
; #define G_STAGE_B(bufoff, p, koff) do { \
;         __builtin_amdgcn_global_load_lds((const unsigned*)(gbase + (size_t)(unsigned)((p) + (koff) + voffB[0])), (LAS unsigned*)(lds + (bufoff) + ldsw), 16, 0, 0); \
;         __builtin_amdgcn_global_load_lds((const unsigned*)(gbase + (size_t)(unsigned)((p) + (koff) + voffB[1])), (LAS unsigned*)(lds + (bufoff) + ldsw + 8192), 16, 0, 0); } while (0)
; #define G_WAIT_V(n) asm volatile("s_waitcnt vmcnt(" #n ")" ::: "memory")
; #define G_BAR __builtin_amdgcn_s_barrier()
; template <class Epi>
; DI void gemm_phase(LAS unsigned char* lds, const Sched& S, const Epi& E, const int K) {
;     ...
;     f32x4 acc[2][2][4][2];
; #pragma unroll
;     for (int a = 0; a < 2; ++a)
; #pragma unroll
;         for (int b = 0; b < 2; ++b)
; #pragma unroll
;             for (int m = 0; m < 4; ++m)
; #pragma unroll
;                 for (int n = 0; n < 2; ++n) acc[a][b][m][n] = (f32x4){0.f, 0.f, 0.f, 0.f};
;     bf16x8 At[4][2], B0[2][2], B1[2][2];
;     ...
;     G_STAGE_B(G_SB(0, 0), cur.b, 0u); G_STAGE_B(G_SB(0, 1), cur.b + hstepB, 0u); G_STAGE_A(G_SA(0, 0), cur.a0, cur.a1, 0u); G_STAGE_A(G_SA(0, 1), cur.a2, cur.a3, 0u);
;     if (wr == 1) G_BAR;
;     G_WAIT_V(2); G_BAR;
;     ...
;     G_STAGE_B(G_SB(0, 0), cur.b, 0u); G_STAGE_A(G_SA(0, 0), cur.a0, cur.a1, 0u); G_STAGE_B(G_SB(0, 1), cur.b + hstepB, 0u); G_STAGE_A(G_SA(0, 1), cur.a2, cur.a3, 0u);
;     if (wr == 1) G_BAR;
;     G_WAIT_V(4); G_BAR;
;     ...
;     G_STAGE_B(G_SB(1, 0), cur.b, kstepB); G_STAGE_A(G_SA(1, 0), cur.a0, cur.a1, kstepA); G_STAGE_B(G_SB(1, 1), cur.b + hstepB, kstepB);
;     G_WAIT_V(6); G_BAR;
.LBB0_207:
	v_lshrrev_b32_e32 v10, 1, v2
	v_and_b32_e32 v10, 24, v10
	v_and_b32_e32 v9, 15, v2
	v_lshlrev_b32_e32 v11, 1, v10
	v_lshlrev_b32_e32 v2, 2, v2
	s_lshl_b32 s7, s7, 5
	v_lshl_or_b32 v131, s9, 6, v9
	v_lshl_or_b32 v9, v9, 6, v11
	s_lshl_b32 s9, s9, 13
	v_and_b32_e32 v2, 32, v2
	s_and_b32 s7, s7, 0x60
	v_bitop3_b32 v11, v9, s9, v2 bitop3:0xde
	s_lshl_b32 s9, s7, 7
	v_bitop3_b32 v133, v9, s9, v2 bitop3:0xde
	s_add_i32 s9, s27, 0x80
	v_add_u32_e32 v2, s9, v128
	s_add_i32 m0, s26, 0x18000
	v_mul_u32_u24_e32 v5, s17, v5
	v_mul_u32_u24_e32 v6, s17, v6
	s_lshr_b32 s17, s18, 8
	s_waitcnt vmcnt(2)
	s_barrier
	global_load_lds_dwordx4 v2, s[82:83]
	v_add_u32_e32 v2, s9, v130
	s_add_i32 m0, s26, 0x1a000
	s_add_i32 s18, s26, 0x8000
	global_load_lds_dwordx4 v2, s[82:83]
	v_add_u32_e32 v2, 0x80, v8
	s_mov_b32 m0, s18
	s_add_i32 s45, s26, 0xa000
	global_load_lds_dwordx4 v2, s[82:83]
	v_add_u32_e32 v2, 0x80, v7
	s_mov_b32 m0, s45
	s_addk_i32 s8, 0x80
	global_load_lds_dwordx4 v2, s[82:83]
	v_add_u32_e32 v2, s8, v128
	s_add_i32 m0, s26, 0x1c000
	v_and_b32_e32 v0, 1, v0
	global_load_lds_dwordx4 v2, s[82:83]
	v_add_u32_e32 v2, s8, v130
	s_add_i32 m0, s26, 0x1e000
	s_add_i32 s46, s17, -2
	global_load_lds_dwordx4 v2, s[82:83]
	s_waitcnt vmcnt(6)
	v_and_b32_e32 v2, 1, v3
	v_lshl_add_u32 v0, v0, 6, v5
	v_lshlrev_b32_e32 v1, 1, v1
	s_cmpk_lt_u32 s6, 0x100
	v_lshl_add_u32 v2, v2, 6, v6
	v_lshlrev_b32_e32 v3, 1, v4
	v_add3_u32 v136, v0, v1, s31
	v_mov_b32_e32 v0, 0
	v_readlane_b32 s6, v253, 19
	s_cselect_b64 s[10:11], -1, 0
	v_or_b32_e32 v134, s7, v10
	v_add3_u32 v135, v2, v3, s31
	s_mov_b32 s50, 0
	v_add_u32_e32 v137, 0, v11
	s_mov_b32 s12, s6
	v_readlane_b32 s47, v253, 18
	v_readlane_b32 s48, v253, 20
	v_mov_b32_e32 v1, v0
	v_mov_b64_e32 v[2:3], 0
	v_mov_b64_e32 v[4:5], 0
	v_mov_b64_e32 v[6:7], 0
	v_mov_b64_e32 v[8:9], 0
	v_mov_b64_e32 v[10:11], 0
	v_mov_b64_e32 v[12:13], 0
	v_mov_b64_e32 v[14:15], 0
	v_mov_b64_e32 v[16:17], 0
	v_mov_b64_e32 v[18:19], 0
	v_mov_b64_e32 v[20:21], 0
	v_mov_b64_e32 v[22:23], 0
	v_mov_b64_e32 v[24:25], 0
	v_mov_b64_e32 v[26:27], 0
	v_mov_b64_e32 v[28:29], 0
	v_mov_b64_e32 v[30:31], 0
	v_mov_b64_e32 v[32:33], 0
	v_mov_b64_e32 v[34:35], 0
	v_mov_b64_e32 v[36:37], 0
	v_mov_b64_e32 v[38:39], 0
	v_mov_b64_e32 v[40:41], 0
	v_mov_b64_e32 v[42:43], 0
	v_mov_b64_e32 v[44:45], 0
	v_mov_b64_e32 v[46:47], 0
	v_mov_b64_e32 v[48:49], 0
	v_mov_b64_e32 v[50:51], 0
	v_mov_b64_e32 v[52:53], 0
	v_mov_b64_e32 v[54:55], 0
	v_mov_b64_e32 v[56:57], 0
	v_mov_b64_e32 v[58:59], 0
	v_mov_b64_e32 v[60:61], 0
	v_mov_b64_e32 v[62:63], 0
	v_mov_b64_e32 v[64:65], 0
	v_mov_b64_e32 v[66:67], 0
	v_mov_b64_e32 v[68:69], 0
	v_mov_b64_e32 v[70:71], 0
	v_mov_b64_e32 v[72:73], 0
	v_mov_b64_e32 v[74:75], 0
	v_mov_b64_e32 v[76:77], 0
	v_mov_b64_e32 v[78:79], 0
	v_mov_b64_e32 v[80:81], 0
	v_mov_b64_e32 v[82:83], 0
	v_mov_b64_e32 v[84:85], 0
	v_mov_b64_e32 v[86:87], 0
	v_mov_b64_e32 v[88:89], 0
	v_mov_b64_e32 v[90:91], 0
	v_mov_b64_e32 v[92:93], 0
	v_mov_b64_e32 v[94:95], 0
	v_mov_b64_e32 v[96:97], 0
	v_mov_b64_e32 v[98:99], 0
	v_mov_b64_e32 v[100:101], 0
	v_mov_b64_e32 v[102:103], 0
	v_mov_b64_e32 v[104:105], 0
	v_mov_b64_e32 v[106:107], 0
	v_mov_b64_e32 v[108:109], 0
	v_mov_b64_e32 v[110:111], 0
	v_mov_b64_e32 v[112:113], 0
	v_mov_b64_e32 v[114:115], 0
	v_mov_b64_e32 v[116:117], 0
	v_mov_b64_e32 v[118:119], 0
	v_mov_b64_e32 v[120:121], 0
	v_mov_b64_e32 v[122:123], 0
	v_mov_b64_e32 v[124:125], 0
	v_mov_b64_e32 v[126:127], 0
	s_barrier
	s_branch .LBB0_210
.LBB0_208:
	v_mov_b32_e32 v0, 0
	s_mov_b32 s12, s55
	s_mov_b32 s47, s54
	s_mov_b32 s48, s56
	s_mov_b32 s27, s57
	s_mov_b32 s36, s58
	s_mov_b32 s37, s59
	s_mov_b32 s38, s60
	s_mov_b32 s35, s61
	s_mov_b32 s50, s66
	v_mov_b32_e32 v1, v0
	v_mov_b64_e32 v[2:3], 0
	v_mov_b64_e32 v[4:5], 0
	v_mov_b64_e32 v[6:7], 0
	v_mov_b64_e32 v[8:9], 0
	v_mov_b64_e32 v[10:11], 0
	v_mov_b64_e32 v[12:13], 0
	v_mov_b64_e32 v[14:15], 0
	v_mov_b64_e32 v[16:17], 0
	v_mov_b64_e32 v[18:19], 0
	v_mov_b64_e32 v[20:21], 0
	v_mov_b64_e32 v[22:23], 0
	v_mov_b64_e32 v[24:25], 0
	v_mov_b64_e32 v[26:27], 0
	v_mov_b64_e32 v[28:29], 0
	v_mov_b64_e32 v[30:31], 0
	v_mov_b64_e32 v[32:33], 0
	v_mov_b64_e32 v[34:35], 0
	v_mov_b64_e32 v[36:37], 0
	v_mov_b64_e32 v[38:39], 0
	v_mov_b64_e32 v[40:41], 0
	v_mov_b64_e32 v[42:43], 0
	v_mov_b64_e32 v[44:45], 0
	v_mov_b64_e32 v[46:47], 0
	v_mov_b64_e32 v[48:49], 0
	v_mov_b64_e32 v[50:51], 0
	v_mov_b64_e32 v[52:53], 0
	v_mov_b64_e32 v[54:55], 0
	v_mov_b64_e32 v[56:57], 0
	v_mov_b64_e32 v[58:59], 0
	v_mov_b64_e32 v[60:61], 0
	v_mov_b64_e32 v[62:63], 0
	v_mov_b64_e32 v[64:65], 0
	v_mov_b64_e32 v[66:67], 0
	v_mov_b64_e32 v[68:69], 0
	v_mov_b64_e32 v[70:71], 0
	v_mov_b64_e32 v[72:73], 0
	v_mov_b64_e32 v[74:75], 0
	v_mov_b64_e32 v[76:77], 0
	v_mov_b64_e32 v[78:79], 0
	v_mov_b64_e32 v[80:81], 0
	v_mov_b64_e32 v[82:83], 0
	v_mov_b64_e32 v[84:85], 0
	v_mov_b64_e32 v[86:87], 0
	v_mov_b64_e32 v[88:89], 0
	v_mov_b64_e32 v[90:91], 0
	v_mov_b64_e32 v[92:93], 0
	v_mov_b64_e32 v[94:95], 0
	v_mov_b64_e32 v[96:97], 0
	v_mov_b64_e32 v[98:99], 0
	v_mov_b64_e32 v[100:101], 0
	v_mov_b64_e32 v[102:103], 0
	v_mov_b64_e32 v[104:105], 0
	v_mov_b64_e32 v[106:107], 0
	v_mov_b64_e32 v[108:109], 0
	v_mov_b64_e32 v[110:111], 0
	v_mov_b64_e32 v[112:113], 0
	v_mov_b64_e32 v[114:115], 0
	v_mov_b64_e32 v[116:117], 0
	v_mov_b64_e32 v[118:119], 0
	v_mov_b64_e32 v[120:121], 0
	v_mov_b64_e32 v[122:123], 0
	v_mov_b64_e32 v[124:125], 0
	v_mov_b64_e32 v[126:127], 0

; #define G_STAGE_A(bufoff, p0, p1, koff) do { \
;         __builtin_amdgcn_global_load_lds((const unsigned*)(gbase + (size_t)(unsigned)((p0) + (koff) + voffA[0])), (LAS unsigned*)(lds + (bufoff) + ldsw), 16, 0, 0); \
;         __builtin_amdgcn_global_load_lds((const unsigned*)(gbase + (size_t)(unsigned)((p1) + (koff) + voffA[1])), (LAS unsigned*)(lds + (bufoff) + ldsw + 8192), 16, 0, 0); } while (0)
; #define G_STAGE_B(bufoff, p, koff) do { \
;         __builtin_amdgcn_global_load_lds((const unsigned*)(gbase + (size_t)(unsigned)((p) + (koff) + voffB[0])), (LAS unsigned*)(lds + (bufoff) + ldsw), 16, 0, 0); \
;         __builtin_amdgcn_global_load_lds((const unsigned*)(gbase + (size_t)(unsigned)((p) + (koff) + voffB[1])), (LAS unsigned*)(lds + (bufoff) + ldsw + 8192), 16, 0, 0); } while (0)
; #define G_WAIT_V(n) asm volatile("s_waitcnt vmcnt(" #n ")" ::: "memory")
; #define G_BAR __builtin_amdgcn_s_barrier()
; template <class Epi>
; DI void gemm_phase(LAS unsigned char* lds, const Sched& S, const Epi& E, const int K) {
;     ...
;     f32x4 acc[2][2][4][2];
; #pragma unroll
;     for (int a = 0; a < 2; ++a)
; #pragma unroll
;         for (int b = 0; b < 2; ++b)
; #pragma unroll
;             for (int m = 0; m < 4; ++m)
; #pragma unroll
;                 for (int n = 0; n < 2; ++n) acc[a][b][m][n] = (f32x4){0.f, 0.f, 0.f, 0.f};
;     bf16x8 At[4][2], B0[2][2], B1[2][2];
;     ...
;     G_STAGE_B(G_SB(0, 0), cur.b, 0u); G_STAGE_B(G_SB(0, 1), cur.b + hstepB, 0u); G_STAGE_A(G_SA(0, 0), cur.a0, cur.a1, 0u); G_STAGE_A(G_SA(0, 1), cur.a2, cur.a3, 0u);
;     if (wr == 1) G_BAR;
;     G_WAIT_V(2); G_BAR;
;     ...
;     G_STAGE_B(G_SB(0, 0), cur.b, 0u); G_STAGE_A(G_SA(0, 0), cur.a0, cur.a1, 0u); G_STAGE_B(G_SB(0, 1), cur.b + hstepB, 0u); G_STAGE_A(G_SA(0, 1), cur.a2, cur.a3, 0u);
;     if (wr == 1) G_BAR;
;     G_WAIT_V(4); G_BAR;
;     ...
;     G_STAGE_B(G_SB(1, 0), cur.b, kstepB); G_STAGE_A(G_SA(1, 0), cur.a0, cur.a1, kstepA); G_STAGE_B(G_SB(1, 1), cur.b + hstepB, kstepB);
;     G_WAIT_V(6); G_BAR;
.LBB0_231:
	v_mov_b32_e32 v5, v185
	v_lshrrev_b32_e32 v3, 1, v1
	s_lshl_b32 s9, s9, 5
	v_lshl_add_u64 v[66:67], s[82:83], 0, v[4:5]
	v_mov_b32_e32 v7, v185
	v_and_b32_e32 v4, 24, v3
	v_lshlrev_b32_e32 v3, 6, v1
	v_lshlrev_b32_e32 v1, 2, v1
	s_and_b32 s14, s9, 0x60
	v_readlane_b32 s9, v253, 26
	v_lshl_add_u64 v[68:69], s[82:83], 0, v[6:7]
	v_and_b32_e32 v6, 32, v1
	v_add_u32_e32 v1, s9, v80
	s_add_i32 m0, s17, 0x18000
	v_and_b32_e32 v82, 0x3c0, v3
	s_waitcnt vmcnt(2)
	s_barrier
	global_load_lds_dwordx4 v1, s[82:83]
	v_add_u32_e32 v1, s9, v81
	s_add_i32 m0, s17, 0x1a000
	v_lshl_or_b32 v5, v4, 1, v82
	s_lshl_b32 s10, s10, 13
	global_load_lds_dwordx4 v1, s[82:83]
	v_ashrrev_i32_e32 v1, 31, v0
	v_bitop3_b32 v7, v5, s10, v6 bitop3:0xde
	v_lshl_add_u64 v[0:1], s[82:83], 0, v[0:1]
	s_mov_b64 s[10:11], 0x250080
	s_add_i32 s21, s17, 0x8000
	v_ashrrev_i32_e32 v3, 31, v2
	v_lshl_add_u64 v[72:73], v[0:1], 0, s[10:11]
	s_mov_b32 m0, s21
	v_lshl_add_u64 v[2:3], s[82:83], 0, v[2:3]
	s_mov_b64 s[10:11], 0x254080
	s_add_i32 s24, s17, 0xa000
	v_mov_b32_e32 v9, v185
	global_load_lds_dwordx4 v[72:73], off
	v_lshl_add_u64 v[74:75], v[2:3], 0, s[10:11]
	s_mov_b32 m0, s24
	v_readlane_b32 s9, v253, 27
	v_lshl_add_u64 v[70:71], s[82:83], 0, v[8:9]
	global_load_lds_dwordx4 v[74:75], off
	v_add_u32_e32 v8, s9, v80
	s_add_i32 m0, s17, 0x1c000
	v_lshl_add_u64 v[64:65], s[82:83], 0, v[184:185]
	global_load_lds_dwordx4 v8, s[82:83]
	v_add_u32_e32 v8, s9, v81
	s_add_i32 m0, s17, 0x1e000
	s_lshl_b32 s9, s14, 7
	global_load_lds_dwordx4 v8, s[82:83]
	v_bitop3_b32 v83, v5, s9, v6 bitop3:0xde
	s_waitcnt vmcnt(6)
	s_cmpk_lt_u32 s8, 0x100
	s_mov_b64 s[8:9], 0x258080
	v_lshl_add_u64 v[76:77], v[0:1], 0, s[8:9]
	s_mov_b64 s[8:9], 0x25c080
	v_mov_b32_e32 v0, 0
	s_cselect_b64 s[12:13], -1, 0
	v_lshl_add_u64 v[78:79], v[2:3], 0, s[8:9]
	s_mov_b32 s35, 0
	v_add_u32_e32 v84, 0, v7
	s_lshl_b32 s48, s14, 1
	v_lshlrev_b32_e32 v184, 1, v4
	v_readlane_b32 s25, v253, 23
	v_readlane_b32 s26, v253, 22
	v_readlane_b32 s27, v253, 24
	v_mov_b32_e32 v1, v0
	v_mov_b64_e32 v[2:3], 0
	v_mov_b64_e32 v[4:5], 0
	v_mov_b64_e32 v[6:7], 0
	v_mov_b64_e32 v[8:9], 0
	v_mov_b64_e32 v[10:11], 0
	v_mov_b64_e32 v[12:13], 0
	v_mov_b64_e32 v[14:15], 0
	v_mov_b64_e32 v[16:17], 0
	v_mov_b64_e32 v[18:19], 0
	v_mov_b64_e32 v[20:21], 0
	v_mov_b64_e32 v[22:23], 0
	v_mov_b64_e32 v[24:25], 0
	v_mov_b64_e32 v[26:27], 0
	v_mov_b64_e32 v[28:29], 0
	v_mov_b64_e32 v[30:31], 0
	v_mov_b64_e32 v[32:33], 0
	v_mov_b64_e32 v[34:35], 0
	v_mov_b64_e32 v[36:37], 0
	v_mov_b64_e32 v[38:39], 0
	v_mov_b64_e32 v[40:41], 0
	v_mov_b64_e32 v[42:43], 0
	v_mov_b64_e32 v[44:45], 0
	v_mov_b64_e32 v[46:47], 0
	v_mov_b64_e32 v[48:49], 0
	v_mov_b64_e32 v[50:51], 0
	v_mov_b64_e32 v[52:53], 0
	v_mov_b64_e32 v[54:55], 0
	v_mov_b64_e32 v[56:57], 0
	v_mov_b64_e32 v[58:59], 0
	v_mov_b64_e32 v[60:61], 0
	v_mov_b64_e32 v[62:63], 0
	s_barrier
	s_branch .LBB0_234
.LBB0_232:
	v_mov_b32_e32 v0, 0
	s_mov_b32 s25, s37
	s_mov_b32 s26, s36
	s_mov_b32 s27, s38
	v_mov_b32_e32 v1, v0
	v_mov_b64_e32 v[2:3], 0
	v_mov_b64_e32 v[4:5], 0
	v_mov_b64_e32 v[6:7], 0
	v_mov_b64_e32 v[8:9], 0
	v_mov_b64_e32 v[10:11], 0
	v_mov_b64_e32 v[12:13], 0
	v_mov_b64_e32 v[14:15], 0
	v_mov_b64_e32 v[16:17], 0
	v_mov_b64_e32 v[18:19], 0
	v_mov_b64_e32 v[20:21], 0
	v_mov_b64_e32 v[22:23], 0
	v_mov_b64_e32 v[24:25], 0
	v_mov_b64_e32 v[26:27], 0
	v_mov_b64_e32 v[28:29], 0
	v_mov_b64_e32 v[30:31], 0
	v_mov_b64_e32 v[32:33], 0
	v_mov_b64_e32 v[34:35], 0
	v_mov_b64_e32 v[36:37], 0
	v_mov_b64_e32 v[38:39], 0
	v_mov_b64_e32 v[40:41], 0
	v_mov_b64_e32 v[42:43], 0
	v_mov_b64_e32 v[44:45], 0
	v_mov_b64_e32 v[46:47], 0
	v_mov_b64_e32 v[48:49], 0
	v_mov_b64_e32 v[50:51], 0
	v_mov_b64_e32 v[52:53], 0
	v_mov_b64_e32 v[54:55], 0
	v_mov_b64_e32 v[56:57], 0
	v_mov_b64_e32 v[58:59], 0
	v_mov_b64_e32 v[60:61], 0
	v_mov_b64_e32 v[62:63], 0
	s_mov_b32 s35, s39

; #define G_STAGE_A(bufoff, p0, p1, koff) do { \
;         __builtin_amdgcn_global_load_lds((const unsigned*)(gbase + (size_t)(unsigned)((p0) + (koff) + voffA[0])), (LAS unsigned*)(lds + (bufoff) + ldsw), 16, 0, 0); \
;         __builtin_amdgcn_global_load_lds((const unsigned*)(gbase + (size_t)(unsigned)((p1) + (koff) + voffA[1])), (LAS unsigned*)(lds + (bufoff) + ldsw + 8192), 16, 0, 0); } while (0)
; #define G_STAGE_B(bufoff, p, koff) do { \
;         __builtin_amdgcn_global_load_lds((const unsigned*)(gbase + (size_t)(unsigned)((p) + (koff) + voffB[0])), (LAS unsigned*)(lds + (bufoff) + ldsw), 16, 0, 0); \
;         __builtin_amdgcn_global_load_lds((const unsigned*)(gbase + (size_t)(unsigned)((p) + (koff) + voffB[1])), (LAS unsigned*)(lds + (bufoff) + ldsw + 8192), 16, 0, 0); } while (0)
; #define G_WAIT_V(n) asm volatile("s_waitcnt vmcnt(" #n ")" ::: "memory")
; #define G_BAR __builtin_amdgcn_s_barrier()
; template <class Epi>
; DI void gemm_phase(LAS unsigned char* lds, const Sched& S, const Epi& E, const int K) {
;     ...
;     f32x4 acc[2][2][4][2];
; #pragma unroll
;     for (int a = 0; a < 2; ++a)
; #pragma unroll
;         for (int b = 0; b < 2; ++b)
; #pragma unroll
;             for (int m = 0; m < 4; ++m)
; #pragma unroll
;                 for (int n = 0; n < 2; ++n) acc[a][b][m][n] = (f32x4){0.f, 0.f, 0.f, 0.f};
;     bf16x8 At[4][2], B0[2][2], B1[2][2];
;     ...
;     G_STAGE_B(G_SB(0, 0), cur.b, 0u); G_STAGE_B(G_SB(0, 1), cur.b + hstepB, 0u); G_STAGE_A(G_SA(0, 0), cur.a0, cur.a1, 0u); G_STAGE_A(G_SA(0, 1), cur.a2, cur.a3, 0u);
;     if (wr == 1) G_BAR;
;     G_WAIT_V(2); G_BAR;
;     ...
;     G_STAGE_B(G_SB(0, 0), cur.b, 0u); G_STAGE_A(G_SA(0, 0), cur.a0, cur.a1, 0u); G_STAGE_B(G_SB(0, 1), cur.b + hstepB, 0u); G_STAGE_A(G_SA(0, 1), cur.a2, cur.a3, 0u);
;     if (wr == 1) G_BAR;
;     G_WAIT_V(4); G_BAR;
;     ...
;     G_STAGE_B(G_SB(1, 0), cur.b, kstepB); G_STAGE_A(G_SA(1, 0), cur.a0, cur.a1, kstepA); G_STAGE_B(G_SB(1, 1), cur.b + hstepB, kstepB);
;     G_WAIT_V(6); G_BAR;
;     ...
; #pragma unroll
;         for (int a = 0; a < 2; ++a)
; #pragma unroll
;             for (int b = 0; b < 2; ++b)
; #pragma unroll
;                 for (int m = 0; m < 4; ++m)
; #pragma unroll
;                     for (int n = 0; n < 2; ++n) acc[a][b][m][n] = (f32x4){0.f, 0.f, 0.f, 0.f};
;         cur = nxt; ++ui;
.LBB0_252:
	v_mov_b32_e32 v5, v185
	v_lshrrev_b32_e32 v3, 1, v1
	v_lshl_add_u64 v[130:131], s[82:83], 0, v[4:5]
	v_and_b32_e32 v172, 15, v1
	v_and_b32_e32 v4, 24, v3
	v_mov_b32_e32 v7, v185
	v_lshlrev_b32_e32 v3, 6, v172
	v_lshlrev_b32_e32 v5, 1, v4
	v_lshlrev_b32_e32 v1, 2, v1
	s_waitcnt vmcnt(0)
	v_lshl_add_u64 v[132:133], s[82:83], 0, v[6:7]
	v_or_b32_e32 v6, v5, v3
	s_lshl_b32 s8, s8, 13
	v_and_b32_e32 v1, 32, v1
	v_bitop3_b32 v3, v5, v1, v3 bitop3:0x36
	v_bitop3_b32 v5, v6, s8, v1 bitop3:0xde
	s_lshl_b32 s8, s7, 12
	s_and_b32 s8, s8, 0x3000
	v_or_b32_e32 v173, s8, v3
	v_readlane_b32 s8, v253, 32
	s_add_i32 m0, s17, 0x18000
	s_waitcnt vmcnt(2)
	s_barrier
	v_add_u32_e32 v1, s8, v170
	global_load_lds_dwordx4 v1, s[82:83]
	v_add_u32_e32 v1, s8, v171
	s_add_i32 m0, s17, 0x1a000
	s_mov_b64 s[8:9], 0x240080
	global_load_lds_dwordx4 v1, s[82:83]
	v_ashrrev_i32_e32 v1, 31, v0
	v_lshl_add_u64 v[0:1], s[82:83], 0, v[0:1]
	s_add_i32 s21, s17, 0x8000
	v_ashrrev_i32_e32 v3, 31, v2
	v_lshl_add_u64 v[136:137], v[0:1], 0, s[8:9]
	s_mov_b32 m0, s21
	v_lshl_add_u64 v[2:3], s[82:83], 0, v[2:3]
	s_mov_b64 s[8:9], 0x244080
	s_add_i32 s24, s17, 0xa000
	global_load_lds_dwordx4 v[136:137], off
	v_lshl_add_u64 v[138:139], v[2:3], 0, s[8:9]
	s_mov_b32 m0, s24
	v_readlane_b32 s8, v253, 33
	global_load_lds_dwordx4 v[138:139], off
	s_nop 0
	v_add_u32_e32 v6, s8, v170
	s_add_i32 m0, s17, 0x1c000
	s_lshl_b32 s12, s7, 5
	global_load_lds_dwordx4 v6, s[82:83]
	v_add_u32_e32 v6, s8, v171
	s_add_i32 m0, s17, 0x1e000
	v_and_or_b32 v4, s12, 32, v4
	global_load_lds_dwordx4 v6, s[82:83]
	v_lshlrev_b32_e32 v6, 3, v4
	v_lshl_add_u64 v[128:129], s[82:83], 0, v[184:185]
	v_lshl_or_b32 v184, v172, 9, v6
	v_or_b32_e32 v174, 16, v172
	s_cmpk_lt_u32 s6, 0x100
	v_lshl_add_u64 v[140:141], s[14:15], 0, v[184:185]
	v_lshl_or_b32 v184, v174, 9, v6
	v_or_b32_e32 v175, 32, v172
	s_waitcnt vmcnt(6)
	s_cselect_b64 s[10:11], -1, 0
	s_lshr_b32 s25, s7, 1
	v_lshl_add_u64 v[142:143], s[14:15], 0, v[184:185]
	v_lshl_or_b32 v184, v175, 9, v6
	v_or_b32_e32 v176, 48, v172
	s_mov_b64 s[6:7], 0x248080
	v_mov_b32_e32 v9, v185
	v_lshl_add_u64 v[144:145], s[14:15], 0, v[184:185]
	v_lshl_or_b32 v184, v176, 9, v6
	v_lshl_add_u64 v[148:149], v[0:1], 0, s[6:7]
	s_mov_b64 s[6:7], 0x24c080
	v_mov_b32_e32 v0, 0
	v_lshl_add_u64 v[134:135], s[82:83], 0, v[8:9]
	v_lshl_add_u64 v[146:147], s[14:15], 0, v[184:185]
	v_lshl_add_u64 v[150:151], v[2:3], 0, s[6:7]
	s_mov_b32 s39, 0
	v_add_u32_e32 v177, 0, v5
	v_lshlrev_b32_e32 v184, 1, v4
	v_readlane_b32 s26, v253, 29
	v_readlane_b32 s27, v253, 28
	v_readlane_b32 s35, v253, 30
	v_mov_b32_e32 v1, v0
	v_mov_b64_e32 v[2:3], 0
	v_mov_b64_e32 v[4:5], 0
	v_mov_b64_e32 v[6:7], 0
	v_mov_b64_e32 v[8:9], 0
	v_mov_b64_e32 v[10:11], 0
	v_mov_b64_e32 v[12:13], 0
	v_mov_b64_e32 v[14:15], 0
	v_mov_b64_e32 v[16:17], 0
	v_mov_b64_e32 v[18:19], 0
	v_mov_b64_e32 v[20:21], 0
	v_mov_b64_e32 v[22:23], 0
	v_mov_b64_e32 v[24:25], 0
	v_mov_b64_e32 v[26:27], 0
	v_mov_b64_e32 v[28:29], 0
	v_mov_b64_e32 v[30:31], 0
	v_mov_b64_e32 v[32:33], 0
	v_mov_b64_e32 v[34:35], 0
	v_mov_b64_e32 v[36:37], 0
	v_mov_b64_e32 v[38:39], 0
	v_mov_b64_e32 v[40:41], 0
	v_mov_b64_e32 v[42:43], 0
	v_mov_b64_e32 v[44:45], 0
	v_mov_b64_e32 v[46:47], 0
	v_mov_b64_e32 v[48:49], 0
	v_mov_b64_e32 v[50:51], 0
	v_mov_b64_e32 v[52:53], 0
	v_mov_b64_e32 v[54:55], 0
	v_mov_b64_e32 v[56:57], 0
	v_mov_b64_e32 v[58:59], 0
	v_mov_b64_e32 v[60:61], 0
	v_mov_b64_e32 v[62:63], 0
	v_mov_b64_e32 v[64:65], 0
	v_mov_b64_e32 v[66:67], 0
	v_mov_b64_e32 v[68:69], 0
	v_mov_b64_e32 v[70:71], 0
	v_mov_b64_e32 v[72:73], 0
	v_mov_b64_e32 v[74:75], 0
	v_mov_b64_e32 v[76:77], 0
	v_mov_b64_e32 v[78:79], 0
	v_mov_b64_e32 v[80:81], 0
	v_mov_b64_e32 v[82:83], 0
	v_mov_b64_e32 v[84:85], 0
	v_mov_b64_e32 v[86:87], 0
	v_mov_b64_e32 v[88:89], 0
	v_mov_b64_e32 v[90:91], 0
	v_mov_b64_e32 v[92:93], 0
	v_mov_b64_e32 v[94:95], 0
	v_mov_b64_e32 v[96:97], 0
	v_mov_b64_e32 v[98:99], 0
	v_mov_b64_e32 v[100:101], 0
	v_mov_b64_e32 v[102:103], 0
	v_mov_b64_e32 v[104:105], 0
	v_mov_b64_e32 v[106:107], 0
	v_mov_b64_e32 v[108:109], 0
	v_mov_b64_e32 v[110:111], 0
	v_mov_b64_e32 v[112:113], 0
	v_mov_b64_e32 v[114:115], 0
	v_mov_b64_e32 v[116:117], 0
	v_mov_b64_e32 v[118:119], 0
	v_mov_b64_e32 v[120:121], 0
	v_mov_b64_e32 v[122:123], 0
	v_mov_b64_e32 v[124:125], 0
	v_mov_b64_e32 v[126:127], 0
	s_barrier
	s_branch .LBB0_255
.LBB0_253:
	v_mov_b32_e32 v0, 0
	s_mov_b32 s26, s37
	s_mov_b32 s27, s36
	s_mov_b32 s35, s38
	v_mov_b32_e32 v1, v0
	v_mov_b64_e32 v[2:3], 0
	v_mov_b64_e32 v[4:5], 0
	v_mov_b64_e32 v[6:7], 0
	v_mov_b64_e32 v[8:9], 0
	v_mov_b64_e32 v[10:11], 0
	v_mov_b64_e32 v[12:13], 0
	v_mov_b64_e32 v[14:15], 0
	v_mov_b64_e32 v[16:17], 0
	v_mov_b64_e32 v[18:19], 0
	v_mov_b64_e32 v[20:21], 0
	v_mov_b64_e32 v[22:23], 0
	v_mov_b64_e32 v[24:25], 0
	v_mov_b64_e32 v[26:27], 0
	v_mov_b64_e32 v[28:29], 0
	v_mov_b64_e32 v[30:31], 0
	v_mov_b64_e32 v[32:33], 0
	v_mov_b64_e32 v[34:35], 0
	v_mov_b64_e32 v[36:37], 0
	v_mov_b64_e32 v[38:39], 0
	v_mov_b64_e32 v[40:41], 0
	v_mov_b64_e32 v[42:43], 0
	v_mov_b64_e32 v[44:45], 0
	v_mov_b64_e32 v[46:47], 0
	v_mov_b64_e32 v[48:49], 0
	v_mov_b64_e32 v[50:51], 0
	v_mov_b64_e32 v[52:53], 0
	v_mov_b64_e32 v[54:55], 0
	v_mov_b64_e32 v[56:57], 0
	v_mov_b64_e32 v[58:59], 0
	v_mov_b64_e32 v[60:61], 0
	v_mov_b64_e32 v[62:63], 0
	v_mov_b64_e32 v[64:65], 0
	v_mov_b64_e32 v[66:67], 0
	v_mov_b64_e32 v[68:69], 0
	v_mov_b64_e32 v[70:71], 0
	v_mov_b64_e32 v[72:73], 0
	v_mov_b64_e32 v[74:75], 0
	v_mov_b64_e32 v[76:77], 0
	v_mov_b64_e32 v[78:79], 0
	v_mov_b64_e32 v[80:81], 0
	v_mov_b64_e32 v[82:83], 0
	v_mov_b64_e32 v[84:85], 0
	v_mov_b64_e32 v[86:87], 0
	v_mov_b64_e32 v[88:89], 0
	v_mov_b64_e32 v[90:91], 0
	v_mov_b64_e32 v[92:93], 0
	v_mov_b64_e32 v[94:95], 0
	v_mov_b64_e32 v[96:97], 0
	v_mov_b64_e32 v[98:99], 0
	v_mov_b64_e32 v[100:101], 0
	v_mov_b64_e32 v[102:103], 0
	v_mov_b64_e32 v[104:105], 0
	v_mov_b64_e32 v[106:107], 0
	v_mov_b64_e32 v[108:109], 0
	v_mov_b64_e32 v[110:111], 0
	v_mov_b64_e32 v[112:113], 0
	v_mov_b64_e32 v[114:115], 0
	v_mov_b64_e32 v[116:117], 0
	v_mov_b64_e32 v[118:119], 0
	v_mov_b64_e32 v[120:121], 0
	v_mov_b64_e32 v[122:123], 0
	v_mov_b64_e32 v[124:125], 0
	v_mov_b64_e32 v[126:127], 0
	s_mov_b32 s39, s41

; #define G_STAGE_A(bufoff, p0, p1, koff) do { \
;         __builtin_amdgcn_global_load_lds((const unsigned*)(gbase + (size_t)(unsigned)((p0) + (koff) + voffA[0])), (LAS unsigned*)(lds + (bufoff) + ldsw), 16, 0, 0); \
;         __builtin_amdgcn_global_load_lds((const unsigned*)(gbase + (size_t)(unsigned)((p1) + (koff) + voffA[1])), (LAS unsigned*)(lds + (bufoff) + ldsw + 8192), 16, 0, 0); } while (0)
; #define G_STAGE_B(bufoff, p, koff) do { \
;         __builtin_amdgcn_global_load_lds((const unsigned*)(gbase + (size_t)(unsigned)((p) + (koff) + voffB[0])), (LAS unsigned*)(lds + (bufoff) + ldsw), 16, 0, 0); \
;         __builtin_amdgcn_global_load_lds((const unsigned*)(gbase + (size_t)(unsigned)((p) + (koff) + voffB[1])), (LAS unsigned*)(lds + (bufoff) + ldsw + 8192), 16, 0, 0); } while (0)
; #define G_WAIT_V(n) asm volatile("s_waitcnt vmcnt(" #n ")" ::: "memory")
; #define G_BAR __builtin_amdgcn_s_barrier()
; template <class Epi>
; DI void gemm_phase(LAS unsigned char* lds, const Sched& S, const Epi& E, const int K) {
;     ...
;     f32x4 acc[2][2][4][2];
; #pragma unroll
;     for (int a = 0; a < 2; ++a)
; #pragma unroll
;         for (int b = 0; b < 2; ++b)
; #pragma unroll
;             for (int m = 0; m < 4; ++m)
; #pragma unroll
;                 for (int n = 0; n < 2; ++n) acc[a][b][m][n] = (f32x4){0.f, 0.f, 0.f, 0.f};
;     bf16x8 At[4][2], B0[2][2], B1[2][2];
;     ...
;     G_STAGE_B(G_SB(0, 0), cur.b, 0u); G_STAGE_B(G_SB(0, 1), cur.b + hstepB, 0u); G_STAGE_A(G_SA(0, 0), cur.a0, cur.a1, 0u); G_STAGE_A(G_SA(0, 1), cur.a2, cur.a3, 0u);
;     if (wr == 1) G_BAR;
;     G_WAIT_V(2); G_BAR;
;     ...
;     G_STAGE_B(G_SB(0, 0), cur.b, 0u); G_STAGE_A(G_SA(0, 0), cur.a0, cur.a1, 0u); G_STAGE_B(G_SB(0, 1), cur.b + hstepB, 0u); G_STAGE_A(G_SA(0, 1), cur.a2, cur.a3, 0u);
;     if (wr == 1) G_BAR;
;     G_WAIT_V(4); G_BAR;
;     ...
;     G_STAGE_B(G_SB(1, 0), cur.b, kstepB); G_STAGE_A(G_SA(1, 0), cur.a0, cur.a1, kstepA); G_STAGE_B(G_SB(1, 1), cur.b + hstepB, kstepB);
;     G_WAIT_V(6); G_BAR;
;     ...
; #pragma unroll
;         for (int a = 0; a < 2; ++a)
; #pragma unroll
;             for (int b = 0; b < 2; ++b)
; #pragma unroll
;                 for (int m = 0; m < 4; ++m)
; #pragma unroll
;                     for (int n = 0; n < 2; ++n) acc[a][b][m][n] = (f32x4){0.f, 0.f, 0.f, 0.f};
;         cur = nxt; ++ui;
.LBB0_271:
	v_lshrrev_b32_e32 v15, 1, v11
	v_and_b32_e32 v15, 24, v15
	v_and_b32_e32 v1, 15, v11
	v_lshlrev_b32_e32 v16, 1, v15
	v_lshlrev_b32_e32 v11, 2, v11
	s_lshl_b32 s7, s7, 5
	v_lshl_or_b32 v3, s8, 6, v1
	v_lshl_or_b32 v1, v1, 6, v16
	s_lshl_b32 s8, s8, 13
	v_and_b32_e32 v11, 32, v11
	s_and_b32 s7, s7, 0x60
	v_bitop3_b32 v16, v1, s8, v11 bitop3:0xde
	s_lshl_b32 s8, s7, 7
	v_bitop3_b32 v136, v1, s8, v11 bitop3:0xde
	v_readlane_b32 s8, v253, 38
	s_add_i32 m0, s17, 0x18000
	s_waitcnt vmcnt(2)
	s_barrier
	v_add_u32_e32 v1, s8, v134
	global_load_lds_dwordx4 v1, s[82:83]
	v_add_u32_e32 v1, s8, v135
	s_add_i32 m0, s17, 0x1a000
	s_mov_b64 s[8:9], 0x200080
	s_add_i32 s21, s17, 0x8000
	global_load_lds_dwordx4 v1, s[82:83]
	v_lshl_add_u64 v[4:5], v[4:5], 0, s[8:9]
	s_mov_b32 m0, s21
	s_mov_b64 s[8:9], 0x210080
	s_add_i32 s24, s17, 0xa000
	global_load_lds_dwordx4 v[4:5], off
	v_lshl_add_u64 v[4:5], v[6:7], 0, s[8:9]
	s_mov_b32 m0, s24
	v_readlane_b32 s8, v253, 39
	global_load_lds_dwordx4 v[4:5], off
	s_nop 0
	v_add_u32_e32 v1, s8, v134
	s_add_i32 m0, s17, 0x1c000
	v_add_u32_e32 v139, 0x220000, v0
	global_load_lds_dwordx4 v1, s[82:83]
	v_add_u32_e32 v1, s8, v135
	s_add_i32 m0, s17, 0x1e000
	v_add_u32_e32 v141, 0x200000, v0
	global_load_lds_dwordx4 v1, s[82:83]
	v_or_b32_e32 v1, s7, v15
	v_and_b32_e32 v0, 1, v12
	v_or_b32_e32 v137, 0x400, v1
	v_lshl_add_u32 v0, v0, 6, v14
	v_lshlrev_b32_e32 v1, 1, v13
	s_mov_b32 s8, 0x230080
	v_add3_u32 v184, v0, v1, s8
	v_and_b32_e32 v0, 1, v8
	s_waitcnt vmcnt(6)
	v_lshl_add_u32 v0, v0, 6, v10
	v_lshlrev_b32_e32 v1, 1, v9
	s_mov_b32 s8, 0x220080
	s_cmpk_lt_u32 s6, 0x100
	v_lshl_add_u64 v[128:129], s[82:83], 0, v[184:185]
	v_add3_u32 v184, v0, v1, s8
	v_mov_b32_e32 v0, 0
	s_cselect_b64 s[6:7], -1, 0
	v_add_u32_e32 v138, 0x8000, v3
	v_add_u32_e32 v140, 0x230000, v2
	v_add_u32_e32 v142, 0x210000, v2
	v_lshl_add_u64 v[130:131], s[82:83], 0, v[184:185]
	s_mov_b32 s26, 0
	v_add_u32_e32 v143, 0, v16
	v_readlane_b32 s25, v253, 34
	v_readlane_b32 s27, v253, 35
	v_readlane_b32 s35, v253, 36
	v_mov_b32_e32 v1, v0
	v_mov_b64_e32 v[2:3], 0
	v_mov_b64_e32 v[4:5], 0
	v_mov_b64_e32 v[6:7], 0
	v_mov_b64_e32 v[8:9], 0
	v_mov_b64_e32 v[10:11], 0
	v_mov_b64_e32 v[12:13], 0
	v_mov_b64_e32 v[14:15], 0
	v_mov_b64_e32 v[16:17], 0
	v_mov_b64_e32 v[18:19], 0
	v_mov_b64_e32 v[20:21], 0
	v_mov_b64_e32 v[22:23], 0
	v_mov_b64_e32 v[24:25], 0
	v_mov_b64_e32 v[26:27], 0
	v_mov_b64_e32 v[28:29], 0
	v_mov_b64_e32 v[30:31], 0
	v_mov_b64_e32 v[32:33], 0
	v_mov_b64_e32 v[34:35], 0
	v_mov_b64_e32 v[36:37], 0
	v_mov_b64_e32 v[38:39], 0
	v_mov_b64_e32 v[40:41], 0
	v_mov_b64_e32 v[42:43], 0
	v_mov_b64_e32 v[44:45], 0
	v_mov_b64_e32 v[46:47], 0
	v_mov_b64_e32 v[48:49], 0
	v_mov_b64_e32 v[50:51], 0
	v_mov_b64_e32 v[52:53], 0
	v_mov_b64_e32 v[54:55], 0
	v_mov_b64_e32 v[56:57], 0
	v_mov_b64_e32 v[58:59], 0
	v_mov_b64_e32 v[60:61], 0
	v_mov_b64_e32 v[62:63], 0
	v_mov_b64_e32 v[64:65], 0
	v_mov_b64_e32 v[66:67], 0
	v_mov_b64_e32 v[68:69], 0
	v_mov_b64_e32 v[70:71], 0
	v_mov_b64_e32 v[72:73], 0
	v_mov_b64_e32 v[74:75], 0
	v_mov_b64_e32 v[76:77], 0
	v_mov_b64_e32 v[78:79], 0
	v_mov_b64_e32 v[80:81], 0
	v_mov_b64_e32 v[82:83], 0
	v_mov_b64_e32 v[84:85], 0
	v_mov_b64_e32 v[86:87], 0
	v_mov_b64_e32 v[88:89], 0
	v_mov_b64_e32 v[90:91], 0
	v_mov_b64_e32 v[92:93], 0
	v_mov_b64_e32 v[94:95], 0
	v_mov_b64_e32 v[96:97], 0
	v_mov_b64_e32 v[98:99], 0
	v_mov_b64_e32 v[100:101], 0
	v_mov_b64_e32 v[102:103], 0
	v_mov_b64_e32 v[104:105], 0
	v_mov_b64_e32 v[106:107], 0
	v_mov_b64_e32 v[108:109], 0
	v_mov_b64_e32 v[110:111], 0
	v_mov_b64_e32 v[112:113], 0
	v_mov_b64_e32 v[114:115], 0
	v_mov_b64_e32 v[116:117], 0
	v_mov_b64_e32 v[118:119], 0
	v_mov_b64_e32 v[120:121], 0
	v_mov_b64_e32 v[122:123], 0
	v_mov_b64_e32 v[124:125], 0
	v_mov_b64_e32 v[126:127], 0
	s_barrier
	s_branch .LBB0_274
.LBB0_272:
	v_mov_b32_e32 v0, 0
	s_mov_b32 s25, s37
	s_mov_b32 s27, s36
	s_mov_b32 s35, s38
	s_mov_b32 s26, s39
	v_mov_b32_e32 v1, v0
	v_mov_b64_e32 v[2:3], 0
	v_mov_b64_e32 v[4:5], 0
	v_mov_b64_e32 v[6:7], 0
	v_mov_b64_e32 v[8:9], 0
	v_mov_b64_e32 v[10:11], 0
	v_mov_b64_e32 v[12:13], 0
	v_mov_b64_e32 v[14:15], 0
	v_mov_b64_e32 v[16:17], 0
	v_mov_b64_e32 v[18:19], 0
	v_mov_b64_e32 v[20:21], 0
	v_mov_b64_e32 v[22:23], 0
	v_mov_b64_e32 v[24:25], 0
	v_mov_b64_e32 v[26:27], 0
	v_mov_b64_e32 v[28:29], 0
	v_mov_b64_e32 v[30:31], 0
	v_mov_b64_e32 v[32:33], 0
	v_mov_b64_e32 v[34:35], 0
	v_mov_b64_e32 v[36:37], 0
	v_mov_b64_e32 v[38:39], 0
	v_mov_b64_e32 v[40:41], 0
	v_mov_b64_e32 v[42:43], 0
	v_mov_b64_e32 v[44:45], 0
	v_mov_b64_e32 v[46:47], 0
	v_mov_b64_e32 v[48:49], 0
	v_mov_b64_e32 v[50:51], 0
	v_mov_b64_e32 v[52:53], 0
	v_mov_b64_e32 v[54:55], 0
	v_mov_b64_e32 v[56:57], 0
	v_mov_b64_e32 v[58:59], 0
	v_mov_b64_e32 v[60:61], 0
	v_mov_b64_e32 v[62:63], 0
	v_mov_b64_e32 v[64:65], 0
	v_mov_b64_e32 v[66:67], 0
	v_mov_b64_e32 v[68:69], 0
	v_mov_b64_e32 v[70:71], 0
	v_mov_b64_e32 v[72:73], 0
	v_mov_b64_e32 v[74:75], 0
	v_mov_b64_e32 v[76:77], 0
	v_mov_b64_e32 v[78:79], 0
	v_mov_b64_e32 v[80:81], 0
	v_mov_b64_e32 v[82:83], 0
	v_mov_b64_e32 v[84:85], 0
	v_mov_b64_e32 v[86:87], 0
	v_mov_b64_e32 v[88:89], 0
	v_mov_b64_e32 v[90:91], 0
	v_mov_b64_e32 v[92:93], 0
	v_mov_b64_e32 v[94:95], 0
	v_mov_b64_e32 v[96:97], 0
	v_mov_b64_e32 v[98:99], 0
	v_mov_b64_e32 v[100:101], 0
	v_mov_b64_e32 v[102:103], 0
	v_mov_b64_e32 v[104:105], 0
	v_mov_b64_e32 v[106:107], 0
	v_mov_b64_e32 v[108:109], 0
	v_mov_b64_e32 v[110:111], 0
	v_mov_b64_e32 v[112:113], 0
	v_mov_b64_e32 v[114:115], 0
	v_mov_b64_e32 v[116:117], 0
	v_mov_b64_e32 v[118:119], 0
	v_mov_b64_e32 v[120:121], 0
	v_mov_b64_e32 v[122:123], 0
	v_mov_b64_e32 v[124:125], 0
	v_mov_b64_e32 v[126:127], 0

; #define G_STAGE_A(bufoff, p0, p1, koff) do { \
;         __builtin_amdgcn_global_load_lds((const unsigned*)(gbase + (size_t)(unsigned)((p0) + (koff) + voffA[0])), (LAS unsigned*)(lds + (bufoff) + ldsw), 16, 0, 0); \
;         __builtin_amdgcn_global_load_lds((const unsigned*)(gbase + (size_t)(unsigned)((p1) + (koff) + voffA[1])), (LAS unsigned*)(lds + (bufoff) + ldsw + 8192), 16, 0, 0); } while (0)
; #define G_STAGE_B(bufoff, p, koff) do { \
;         __builtin_amdgcn_global_load_lds((const unsigned*)(gbase + (size_t)(unsigned)((p) + (koff) + voffB[0])), (LAS unsigned*)(lds + (bufoff) + ldsw), 16, 0, 0); \
;         __builtin_amdgcn_global_load_lds((const unsigned*)(gbase + (size_t)(unsigned)((p) + (koff) + voffB[1])), (LAS unsigned*)(lds + (bufoff) + ldsw + 8192), 16, 0, 0); } while (0)
; #define G_WAIT_V(n) asm volatile("s_waitcnt vmcnt(" #n ")" ::: "memory")
; #define G_BAR __builtin_amdgcn_s_barrier()
; template <class Epi>
; DI void gemm_phase(LAS unsigned char* lds, const Sched& S, const Epi& E, const int K) {
;     ...
;     f32x4 acc[2][2][4][2];
; #pragma unroll
;     for (int a = 0; a < 2; ++a)
; #pragma unroll
;         for (int b = 0; b < 2; ++b)
; #pragma unroll
;             for (int m = 0; m < 4; ++m)
; #pragma unroll
;                 for (int n = 0; n < 2; ++n) acc[a][b][m][n] = (f32x4){0.f, 0.f, 0.f, 0.f};
;     bf16x8 At[4][2], B0[2][2], B1[2][2];
;     ...
;     G_STAGE_B(G_SB(0, 0), cur.b, 0u); G_STAGE_B(G_SB(0, 1), cur.b + hstepB, 0u); G_STAGE_A(G_SA(0, 0), cur.a0, cur.a1, 0u); G_STAGE_A(G_SA(0, 1), cur.a2, cur.a3, 0u);
;     if (wr == 1) G_BAR;
;     G_WAIT_V(2); G_BAR;
;     ...
;     G_STAGE_B(G_SB(0, 0), cur.b, 0u); G_STAGE_A(G_SA(0, 0), cur.a0, cur.a1, 0u); G_STAGE_B(G_SB(0, 1), cur.b + hstepB, 0u); G_STAGE_A(G_SA(0, 1), cur.a2, cur.a3, 0u);
;     if (wr == 1) G_BAR;
;     G_WAIT_V(4); G_BAR;
;     ...
;     G_STAGE_B(G_SB(1, 0), cur.b, kstepB); G_STAGE_A(G_SA(1, 0), cur.a0, cur.a1, kstepA); G_STAGE_B(G_SB(1, 1), cur.b + hstepB, kstepB);
;     G_WAIT_V(6); G_BAR;
;     ...
; #pragma unroll
;         for (int a = 0; a < 2; ++a)
; #pragma unroll
;             for (int b = 0; b < 2; ++b)
; #pragma unroll
;                 for (int m = 0; m < 4; ++m)
; #pragma unroll
;                     for (int n = 0; n < 2; ++n) acc[a][b][m][n] = (f32x4){0.f, 0.f, 0.f, 0.f};
;         cur = nxt; ++ui;
.LBB0_305:
	v_lshrrev_b32_e32 v2, 1, v0
	v_and_b32_e32 v2, 24, v2
	v_and_b32_e32 v1, 15, v0
	v_lshlrev_b32_e32 v3, 1, v2
	v_lshlrev_b32_e32 v0, 2, v0
	s_waitcnt vmcnt(0)
	v_lshl_or_b32 v132, s8, 6, v1
	v_lshl_or_b32 v1, v1, 6, v3
	s_lshl_b32 s8, s8, 13
	v_and_b32_e32 v0, 32, v0
	v_bitop3_b32 v3, v1, s8, v0 bitop3:0xde
	s_lshl_b32 s8, s24, 5
	s_and_b32 s8, s8, 0x60
	s_lshl_b32 s24, s8, 7
	v_bitop3_b32 v133, v1, s24, v0 bitop3:0xde
	s_add_i32 s24, s41, 0x80
	v_add_u32_e32 v0, s24, v129
	s_add_i32 m0, s46, 0x18000
	s_waitcnt vmcnt(2)
	s_barrier
	global_load_lds_dwordx4 v0, s[82:83]
	v_add_u32_e32 v0, s24, v131
	s_add_i32 m0, s46, 0x1a000
	v_add_u32_e32 v134, 0x80, v128
	s_add_i32 s59, s46, 0x8000
	global_load_lds_dwordx4 v0, s[82:83]
	v_add_u32_e32 v0, s55, v134
	s_mov_b32 m0, s59
	s_add_i32 s60, s46, 0xa000
	global_load_lds_dwordx4 v0, s[82:83]
	v_add_u32_e32 v0, s55, v130
	v_add_u32_e32 v0, 0x4080, v0
	s_mov_b32 m0, s60
	s_addk_i32 s9, 0x80
	global_load_lds_dwordx4 v0, s[82:83]
	v_add_u32_e32 v0, s9, v129
	s_add_i32 m0, s46, 0x1c000
	v_or_b32_e32 v135, s8, v2
	global_load_lds_dwordx4 v0, s[82:83]
	v_add_u32_e32 v0, s9, v131
	s_add_i32 m0, s46, 0x1e000
	s_cmpk_lt_u32 s11, 0x100
	global_load_lds_dwordx4 v0, s[82:83]
	s_waitcnt vmcnt(6)
	s_cselect_b64 s[24:25], -1, 0
	s_and_b64 s[8:9], s[14:15], exec
	v_mov_b32_e32 v0, 0
	v_or_b32_e32 v136, 16, v132
	v_or_b32_e32 v137, 32, v132
	v_or_b32_e32 v138, 48, v132
	v_add_u32_e32 v139, 0x80, v130
	s_cselect_b32 s61, 7, 3
	s_or_b32 s66, s10, 1
	s_mov_b32 s67, 0
	v_add_u32_e32 v140, 0, v3
	v_mov_b32_e32 v1, v0
	v_mov_b64_e32 v[2:3], 0
	v_mov_b64_e32 v[4:5], 0
	v_mov_b64_e32 v[6:7], 0
	v_mov_b64_e32 v[8:9], 0
	v_mov_b64_e32 v[10:11], 0
	v_mov_b64_e32 v[12:13], 0
	v_mov_b64_e32 v[14:15], 0
	v_mov_b64_e32 v[16:17], 0
	v_mov_b64_e32 v[18:19], 0
	v_mov_b64_e32 v[20:21], 0
	v_mov_b64_e32 v[22:23], 0
	v_mov_b64_e32 v[24:25], 0
	v_mov_b64_e32 v[26:27], 0
	v_mov_b64_e32 v[28:29], 0
	v_mov_b64_e32 v[30:31], 0
	v_mov_b64_e32 v[32:33], 0
	v_mov_b64_e32 v[34:35], 0
	v_mov_b64_e32 v[36:37], 0
	v_mov_b64_e32 v[38:39], 0
	v_mov_b64_e32 v[40:41], 0
	v_mov_b64_e32 v[42:43], 0
	v_mov_b64_e32 v[44:45], 0
	v_mov_b64_e32 v[46:47], 0
	v_mov_b64_e32 v[48:49], 0
	v_mov_b64_e32 v[50:51], 0
	v_mov_b64_e32 v[52:53], 0
	v_mov_b64_e32 v[54:55], 0
	v_mov_b64_e32 v[56:57], 0
	v_mov_b64_e32 v[58:59], 0
	v_mov_b64_e32 v[60:61], 0
	v_mov_b64_e32 v[62:63], 0
	v_mov_b64_e32 v[64:65], 0
	v_mov_b64_e32 v[66:67], 0
	v_mov_b64_e32 v[68:69], 0
	v_mov_b64_e32 v[70:71], 0
	v_mov_b64_e32 v[72:73], 0
	v_mov_b64_e32 v[74:75], 0
	v_mov_b64_e32 v[76:77], 0
	v_mov_b64_e32 v[78:79], 0
	v_mov_b64_e32 v[80:81], 0
	v_mov_b64_e32 v[82:83], 0
	v_mov_b64_e32 v[84:85], 0
	v_mov_b64_e32 v[86:87], 0
	v_mov_b64_e32 v[88:89], 0
	v_mov_b64_e32 v[90:91], 0
	v_mov_b64_e32 v[92:93], 0
	v_mov_b64_e32 v[94:95], 0
	v_mov_b64_e32 v[96:97], 0
	v_mov_b64_e32 v[98:99], 0
	v_mov_b64_e32 v[100:101], 0
	v_mov_b64_e32 v[102:103], 0
	v_mov_b64_e32 v[104:105], 0
	v_mov_b64_e32 v[106:107], 0
	v_mov_b64_e32 v[108:109], 0
	v_mov_b64_e32 v[110:111], 0
	v_mov_b64_e32 v[112:113], 0
	v_mov_b64_e32 v[114:115], 0
	v_mov_b64_e32 v[116:117], 0
	v_mov_b64_e32 v[118:119], 0
	v_mov_b64_e32 v[120:121], 0
	v_mov_b64_e32 v[122:123], 0
	v_mov_b64_e32 v[124:125], 0
	v_mov_b64_e32 v[126:127], 0
	s_barrier
	s_branch .LBB0_308
.LBB0_306:
	v_mov_b32_e32 v0, 0
	s_mov_b32 s39, s69
	s_mov_b32 s38, s68
	s_mov_b32 s41, s70
	s_mov_b32 s47, s71
	s_mov_b32 s50, s72
	s_mov_b32 s54, s73
	s_mov_b32 s55, s75
	s_mov_b32 s67, s78
	v_mov_b32_e32 v1, v0
	v_mov_b64_e32 v[2:3], 0
	v_mov_b64_e32 v[4:5], 0
	v_mov_b64_e32 v[6:7], 0
	v_mov_b64_e32 v[8:9], 0
	v_mov_b64_e32 v[10:11], 0
	v_mov_b64_e32 v[12:13], 0
	v_mov_b64_e32 v[14:15], 0
	v_mov_b64_e32 v[16:17], 0
	v_mov_b64_e32 v[18:19], 0
	v_mov_b64_e32 v[20:21], 0
	v_mov_b64_e32 v[22:23], 0
	v_mov_b64_e32 v[24:25], 0
	v_mov_b64_e32 v[26:27], 0
	v_mov_b64_e32 v[28:29], 0
	v_mov_b64_e32 v[30:31], 0
	v_mov_b64_e32 v[32:33], 0
	v_mov_b64_e32 v[34:35], 0
	v_mov_b64_e32 v[36:37], 0
	v_mov_b64_e32 v[38:39], 0
	v_mov_b64_e32 v[40:41], 0
	v_mov_b64_e32 v[42:43], 0
	v_mov_b64_e32 v[44:45], 0
	v_mov_b64_e32 v[46:47], 0
	v_mov_b64_e32 v[48:49], 0
	v_mov_b64_e32 v[50:51], 0
	v_mov_b64_e32 v[52:53], 0
	v_mov_b64_e32 v[54:55], 0
	v_mov_b64_e32 v[56:57], 0
	v_mov_b64_e32 v[58:59], 0
	v_mov_b64_e32 v[60:61], 0
	v_mov_b64_e32 v[62:63], 0
	v_mov_b64_e32 v[64:65], 0
	v_mov_b64_e32 v[66:67], 0
	v_mov_b64_e32 v[68:69], 0
	v_mov_b64_e32 v[70:71], 0
	v_mov_b64_e32 v[72:73], 0
	v_mov_b64_e32 v[74:75], 0
	v_mov_b64_e32 v[76:77], 0
	v_mov_b64_e32 v[78:79], 0
	v_mov_b64_e32 v[80:81], 0
	v_mov_b64_e32 v[82:83], 0
	v_mov_b64_e32 v[84:85], 0
	v_mov_b64_e32 v[86:87], 0
	v_mov_b64_e32 v[88:89], 0
	v_mov_b64_e32 v[90:91], 0
	v_mov_b64_e32 v[92:93], 0
	v_mov_b64_e32 v[94:95], 0
	v_mov_b64_e32 v[96:97], 0
	v_mov_b64_e32 v[98:99], 0
	v_mov_b64_e32 v[100:101], 0
	v_mov_b64_e32 v[102:103], 0
	v_mov_b64_e32 v[104:105], 0
	v_mov_b64_e32 v[106:107], 0
	v_mov_b64_e32 v[108:109], 0
	v_mov_b64_e32 v[110:111], 0
	v_mov_b64_e32 v[112:113], 0
	v_mov_b64_e32 v[114:115], 0
	v_mov_b64_e32 v[116:117], 0
	v_mov_b64_e32 v[118:119], 0
	v_mov_b64_e32 v[120:121], 0
	v_mov_b64_e32 v[122:123], 0
	v_mov_b64_e32 v[124:125], 0
	v_mov_b64_e32 v[126:127], 0

; DI void attn_phase(LAS unsigned char* lds, ArgsRef a, int l, int vcu, int G) {
;     ...
;                 float mx = -1e30f;
;                 if (loc) {
;                     const int tb = (h * 15 + (kr - row) + 7) * 31 + 15 - qcol + 32 * cb + 8 * hg;
;                     const int kc0 = 32 * cb + 8 * hg;
; #pragma unroll
;                     for (int r = 0; r < 4; ++r)
; #pragma unroll
;                         for (int i = 0; i < 4; ++i) {
;                             const int kt = 16 * (r >> 1) + 4 * (r & 1) + i, kc = kc0 + kt;
;                             const bool valid = (kc >= cs) && (kc < cs + 16);
;                             const float bias = tab[valid ? tb + kt : 0];
;                             const float v = valid ? s[4 * r + i] * SC + bias : -1e30f;
;                             s[4 * r + i] = v; mx = fmaxf(mx, v);
;                         }
;                 } else {
; #pragma unroll
;                     for (int i = 0; i < 16; ++i) { const float v = s[i] * SC; s[i] = v; mx = fmaxf(mx, v); }
;                 }
;                 mx = fmaxf(mx, __shfl_xor(mx, 32));
.LBB0_352:
	s_waitcnt vmcnt(7) lgkmcnt(7)
	v_mfma_f32_32x32x16_bf16 v[64:79], v[144:147], v[96:99], 0
	s_mov_b64 s[6:7], -1
	s_and_b64 vcc, exec, s[8:9]
	s_waitcnt vmcnt(6) lgkmcnt(6)
	v_mfma_f32_32x32x16_bf16 v[64:79], v[148:151], v[100:103], v[64:79]
	s_waitcnt vmcnt(3) lgkmcnt(5)
	v_mfma_f32_32x32x16_bf16 v[64:79], v[152:155], v[112:115], v[64:79]
	s_waitcnt vmcnt(2) lgkmcnt(4)
	v_mfma_f32_32x32x16_bf16 v[64:79], v[156:159], v[116:119], v[64:79]
	s_cbranch_vccz .LBB0_386
	s_add_i32 s6, s39, s37
	s_lshl_b32 s12, s38, 5
	s_mul_i32 s6, s6, 31
	v_or_b32_e32 v90, s12, v217
	v_sub_u32_e32 v89, s6, v205
	s_lshl_b32 s13, s12, 2
	v_add_u32_e32 v89, v89, v217
	v_lshl_add_u32 v89, v89, 2, s13
	ds_read_b32 v80, v89 offset:928
	ds_read_b32 v81, v89 offset:932
	ds_read_b32 v82, v89 offset:936
	ds_read_b32 v83, v89 offset:940
	ds_read_b32 v84, v89 offset:944
	ds_read_b32 v85, v89 offset:948
	ds_read_b32 v86, v89 offset:952
	ds_read_b32 v87, v89 offset:956
	s_cmp_lg_u32 s38, 0
	s_cbranch_scc1 .LattnA_rd
	ds_read_b32 v206, v89 offset:992
	ds_read_b32 v207, v89 offset:996
	ds_read_b32 v208, v89 offset:1000
	ds_read_b32 v209, v89 offset:1004
	ds_read_b32 v210, v89 offset:1008
	ds_read_b32 v211, v89 offset:1012
	ds_read_b32 v212, v89 offset:1016
	ds_read_b32 v213, v89 offset:1020
.LattnA_rd:
	v_sub_u32_e32 v90, v90, v215
	v_add_u32_e32 v90, 32, v90
	v_med3_i32 v90, v90, 0, 63
	v_mov_b32_e32 v94, 0
	v_mov_b32_e32 v95, 0xffff
	v_lshrrev_b64 v[92:93], v90, v[94:95]
	s_waitcnt lgkmcnt(0)
	v_fmac_f32_e32 v80, 0x3e38aa3b, v64
	v_bfe_i32 v93, v92, 0, 1
	v_bfi_b32 v80, v93, v80, s52
	v_fmac_f32_e32 v81, 0x3e38aa3b, v65
	v_bfe_i32 v93, v92, 1, 1
	v_bfi_b32 v81, v93, v81, s52
	v_fmac_f32_e32 v82, 0x3e38aa3b, v66
	v_bfe_i32 v93, v92, 2, 1
	v_bfi_b32 v82, v93, v82, s52
	v_fmac_f32_e32 v83, 0x3e38aa3b, v67
	v_bfe_i32 v93, v92, 3, 1
	v_bfi_b32 v83, v93, v83, s52
	v_fmac_f32_e32 v84, 0x3e38aa3b, v68
	v_bfe_i32 v93, v92, 4, 1
	v_bfi_b32 v84, v93, v84, s52
	v_fmac_f32_e32 v85, 0x3e38aa3b, v69
	v_bfe_i32 v93, v92, 5, 1
	v_bfi_b32 v85, v93, v85, s52
	v_fmac_f32_e32 v86, 0x3e38aa3b, v70
	v_bfe_i32 v93, v92, 6, 1
	v_bfi_b32 v86, v93, v86, s52
	v_fmac_f32_e32 v87, 0x3e38aa3b, v71
	v_bfe_i32 v93, v92, 7, 1
	v_bfi_b32 v87, v93, v87, s52
	v_max3_f32 v89, v80, s52, v81
	v_max3_f32 v89, v89, v82, v83
	v_max3_f32 v89, v89, v84, v85
	v_max3_f32 v89, v89, v86, v87
	s_cmp_lg_u32 s38, 0
	s_cbranch_scc1 .LattnA_done
	v_fmac_f32_e32 v206, 0x3e38aa3b, v72
	v_bfe_i32 v93, v92, 16, 1
	v_bfi_b32 v206, v93, v206, s52
	v_fmac_f32_e32 v207, 0x3e38aa3b, v73
	v_bfe_i32 v93, v92, 17, 1
	v_bfi_b32 v207, v93, v207, s52
	v_fmac_f32_e32 v208, 0x3e38aa3b, v74
	v_bfe_i32 v93, v92, 18, 1
	v_bfi_b32 v208, v93, v208, s52
	v_fmac_f32_e32 v209, 0x3e38aa3b, v75
	v_bfe_i32 v93, v92, 19, 1
	v_bfi_b32 v209, v93, v209, s52
	v_fmac_f32_e32 v210, 0x3e38aa3b, v76
	v_bfe_i32 v93, v92, 20, 1
	v_bfi_b32 v210, v93, v210, s52
	v_fmac_f32_e32 v211, 0x3e38aa3b, v77
	v_bfe_i32 v93, v92, 21, 1
	v_bfi_b32 v211, v93, v211, s52
	v_fmac_f32_e32 v212, 0x3e38aa3b, v78
	v_bfe_i32 v93, v92, 22, 1
	v_bfi_b32 v212, v93, v212, s52
	v_fmac_f32_e32 v213, 0x3e38aa3b, v79
	v_bfe_i32 v93, v92, 23, 1
	v_bfi_b32 v213, v93, v213, s52
	v_max3_f32 v89, v89, v206, v207
	v_max3_f32 v89, v89, v208, v209
	v_max3_f32 v89, v89, v210, v211
	v_max3_f32 v89, v89, v212, v213
.LattnA_done:
	s_mov_b64 s[6:7], 0
.LBB0_386:
	s_and_b64 vcc, exec, s[6:7]
	s_cbranch_vccz .LBB0_388
	s_nop 8
	v_pk_mul_f32 v[80:81], v[64:65], s[30:31] op_sel_hi:[1,0]
	v_pk_mul_f32 v[82:83], v[66:67], s[30:31] op_sel_hi:[1,0]
	v_max3_f32 v64, v80, s52, v81
	v_max3_f32 v64, v64, v82, v83
	v_pk_mul_f32 v[84:85], v[68:69], s[30:31] op_sel_hi:[1,0]
	v_pk_mul_f32 v[86:87], v[70:71], s[30:31] op_sel_hi:[1,0]
	v_max3_f32 v64, v64, v84, v85
	v_max3_f32 v64, v64, v86, v87
	v_pk_mul_f32 v[206:207], v[72:73], s[30:31] op_sel_hi:[1,0]
	v_pk_mul_f32 v[208:209], v[74:75], s[30:31] op_sel_hi:[1,0]
	v_max3_f32 v64, v64, v206, v207
	v_max3_f32 v64, v64, v208, v209
	v_pk_mul_f32 v[210:211], v[76:77], s[30:31] op_sel_hi:[1,0]
	v_pk_mul_f32 v[212:213], v[78:79], s[30:31] op_sel_hi:[1,0]
	v_max3_f32 v64, v64, v210, v211
	v_max3_f32 v89, v64, v212, v213

; DI unsigned pk2(float lo, float hi) { f32x2 v = {lo, hi}; return __builtin_bit_cast(unsigned, __builtin_convertvector(v, bf16x2v)); }
; #define MFMA32(a, b, c) __builtin_amdgcn_mfma_f32_32x32x16_bf16((a), (b), (c), 0, 0, 0)
; DI void attn_phase(LAS unsigned char* lds, ArgsRef a, int l, int vcu, int G) {
;     ...
;                 auto pv_chunk = [&](auto JC) { constexpr int J = decltype(JC)::value;
;                     float ps = 0.f;
; #pragma unroll
;                     for (int i = 0; i < 8; ++i) { const float p = __builtin_amdgcn_exp2f(s[8 * J + i] - mnew); s[8 * J + i] = p; ps += p; }
;                     u32x4 pw; pw.x = pk2(s[8 * J + 0], s[8 * J + 1]); pw.y = pk2(s[8 * J + 2], s[8 * J + 3]); pw.z = pk2(s[8 * J + 4], s[8 * J + 5]); pw.w = pk2(s[8 * J + 6], s[8 * J + 7]);
;                     const bf16x8 pf = __builtin_bit_cast(bf16x8, pw);
;                     o0 = MFMA32(vf[0][J], pf, o0);
;                     o1 = MFMA32(vf[1][J], pf, o1);
;                     return ps; };
.LBB0_390:
	v_sub_f32_e32 v64, v80, v250
	v_exp_f32_e32 v251, v64
	v_sub_f32_e32 v64, v81, v250
	v_exp_f32_e32 v252, v64
	v_sub_f32_e32 v64, v82, v250
	v_exp_f32_e32 v229, v64
	v_sub_f32_e32 v64, v83, v250
	v_exp_f32_e32 v234, v64
	v_sub_f32_e32 v64, v84, v250
	v_exp_f32_e32 v235, v64
	v_sub_f32_e32 v64, v85, v250
	v_exp_f32_e32 v236, v64
	v_sub_f32_e32 v64, v86, v250
	v_exp_f32_e32 v237, v64
	v_sub_f32_e32 v64, v87, v250
	v_exp_f32_e32 v233, v64
	s_cmp_lg_u32 s38, 0
	s_cselect_b64 s[12:13], -1, 0
	s_xor_b64 s[10:11], s[10:11], -1
	s_and_b64 s[12:13], s[10:11], s[12:13]
	s_mov_b64 s[6:7], -1
	v_cvt_pk_bf16_f32 v160, v251, v252
	v_cvt_pk_bf16_f32 v161, v229, v234
	v_cvt_pk_bf16_f32 v162, v235, v236
	v_cvt_pk_bf16_f32 v163, v237, v233
	s_and_b64 vcc, exec, s[12:13]
	s_cbranch_vccz .LBB0_392
	v_mfma_f32_32x32x16_bf16 v[32:47], v[136:139], v[160:163], v[32:47]
	s_mov_b64 s[6:7], 0
	s_waitcnt vmcnt(1)
	v_mfma_f32_32x32x16_bf16 v[48:63], v[140:143], v[160:163], v[48:63]

; DI void attn_phase(LAS unsigned char* lds, ArgsRef a, int l, int vcu, int G) {
;     ...
;                 float mx = -1e30f;
;                 if (loc) {
;                     const int tb = (h * 15 + (kr - row) + 7) * 31 + 15 - qcol + 32 * cb + 8 * hg;
;                     const int kc0 = 32 * cb + 8 * hg;
; #pragma unroll
;                     for (int r = 0; r < 4; ++r)
; #pragma unroll
;                         for (int i = 0; i < 4; ++i) {
;                             const int kt = 16 * (r >> 1) + 4 * (r & 1) + i, kc = kc0 + kt;
;                             const bool valid = (kc >= cs) && (kc < cs + 16);
;                             const float bias = tab[valid ? tb + kt : 0];
;                             const float v = valid ? s[4 * r + i] * SC + bias : -1e30f;
;                             s[4 * r + i] = v; mx = fmaxf(mx, v);
;                         }
;                 } else {
; #pragma unroll
;                     for (int i = 0; i < 16; ++i) { const float v = s[i] * SC; s[i] = v; mx = fmaxf(mx, v); }
;                 }
;                 mx = fmaxf(mx, __shfl_xor(mx, 32));
;     ...
;                 if (!loc || cb == HALF) { ps = pv_chunk(std::integral_constant<int, 0>{}); ps += pv_chunk(std::integral_constant<int, 1>{}); }
.LBB0_395:
	s_nop 1
	s_andn2_b64 vcc, exec, s[0:1]
	s_cbranch_vccnz .LBB0_394
.LBB0_396:
	v_mfma_f32_32x32x16_bf16 v[64:79], v[144:147], v[104:107], 0
	s_mov_b64 s[6:7], -1
	s_and_b64 vcc, exec, s[8:9]
	v_mfma_f32_32x32x16_bf16 v[64:79], v[148:151], v[108:111], v[64:79]
	s_waitcnt vmcnt(1)
	v_mfma_f32_32x32x16_bf16 v[64:79], v[152:155], v[120:123], v[64:79]
	s_waitcnt vmcnt(0)
	v_mfma_f32_32x32x16_bf16 v[64:79], v[156:159], v[124:127], v[64:79]
	s_cbranch_vccz .LBB0_430
	s_add_i32 s6, s39, s37
	s_lshl_b32 s8, s38, 5
	s_mul_i32 s6, s6, 31
	v_or_b32_e32 v90, s8, v217
	v_sub_u32_e32 v88, s6, v205
	s_lshl_b32 s9, s8, 2
	v_add_u32_e32 v88, v88, v217
	v_lshl_add_u32 v88, v88, 2, s9
	ds_read_b32 v80, v88 offset:864
	ds_read_b32 v81, v88 offset:868
	ds_read_b32 v82, v88 offset:872
	ds_read_b32 v83, v88 offset:876
	ds_read_b32 v84, v88 offset:880
	ds_read_b32 v85, v88 offset:884
	ds_read_b32 v86, v88 offset:888
	ds_read_b32 v87, v88 offset:892
	s_cmp_eq_u32 s38, 0
	s_cbranch_scc1 .LattnB_rd
	ds_read_b32 v144, v88 offset:800
	ds_read_b32 v145, v88 offset:804
	ds_read_b32 v146, v88 offset:808
	ds_read_b32 v147, v88 offset:812
	ds_read_b32 v148, v88 offset:816
	ds_read_b32 v149, v88 offset:820
	ds_read_b32 v150, v88 offset:824
	ds_read_b32 v151, v88 offset:828
.LattnB_rd:
	v_sub_u32_e32 v90, v90, v219
	v_add_u32_e32 v90, 32, v90
	v_med3_i32 v90, v90, 0, 63
	v_mov_b32_e32 v94, 0
	v_mov_b32_e32 v95, 0xffff
	v_lshrrev_b64 v[92:93], v90, v[94:95]
	s_waitcnt lgkmcnt(0)
	v_fmac_f32_e32 v80, 0x3e38aa3b, v72
	v_bfe_i32 v93, v92, 16, 1
	v_bfi_b32 v80, v93, v80, s52
	v_fmac_f32_e32 v81, 0x3e38aa3b, v73
	v_bfe_i32 v93, v92, 17, 1
	v_bfi_b32 v81, v93, v81, s52
	v_fmac_f32_e32 v82, 0x3e38aa3b, v74
	v_bfe_i32 v93, v92, 18, 1
	v_bfi_b32 v82, v93, v82, s52
	v_fmac_f32_e32 v83, 0x3e38aa3b, v75
	v_bfe_i32 v93, v92, 19, 1
	v_bfi_b32 v83, v93, v83, s52
	v_fmac_f32_e32 v84, 0x3e38aa3b, v76
	v_bfe_i32 v93, v92, 20, 1
	v_bfi_b32 v84, v93, v84, s52
	v_fmac_f32_e32 v85, 0x3e38aa3b, v77
	v_bfe_i32 v93, v92, 21, 1
	v_bfi_b32 v85, v93, v85, s52
	v_fmac_f32_e32 v86, 0x3e38aa3b, v78
	v_bfe_i32 v93, v92, 22, 1
	v_bfi_b32 v86, v93, v86, s52
	v_fmac_f32_e32 v87, 0x3e38aa3b, v79
	v_bfe_i32 v93, v92, 23, 1
	v_bfi_b32 v87, v93, v87, s52
	v_max3_f32 v88, v80, s52, v81
	v_max3_f32 v88, v88, v82, v83
	v_max3_f32 v88, v88, v84, v85
	v_max3_f32 v88, v88, v86, v87
	s_cmp_eq_u32 s38, 0
	s_cbranch_scc1 .LattnB_done
	v_fmac_f32_e32 v144, 0x3e38aa3b, v64
	v_bfe_i32 v93, v92, 0, 1
	v_bfi_b32 v144, v93, v144, s52
	v_fmac_f32_e32 v145, 0x3e38aa3b, v65
	v_bfe_i32 v93, v92, 1, 1
	v_bfi_b32 v145, v93, v145, s52
	v_fmac_f32_e32 v146, 0x3e38aa3b, v66
	v_bfe_i32 v93, v92, 2, 1
	v_bfi_b32 v146, v93, v146, s52
	v_fmac_f32_e32 v147, 0x3e38aa3b, v67
	v_bfe_i32 v93, v92, 3, 1
	v_bfi_b32 v147, v93, v147, s52
	v_fmac_f32_e32 v148, 0x3e38aa3b, v68
	v_bfe_i32 v93, v92, 4, 1
	v_bfi_b32 v148, v93, v148, s52
	v_fmac_f32_e32 v149, 0x3e38aa3b, v69
	v_bfe_i32 v93, v92, 5, 1
	v_bfi_b32 v149, v93, v149, s52
	v_fmac_f32_e32 v150, 0x3e38aa3b, v70
	v_bfe_i32 v93, v92, 6, 1
	v_bfi_b32 v150, v93, v150, s52
	v_fmac_f32_e32 v151, 0x3e38aa3b, v71
	v_bfe_i32 v93, v92, 7, 1
	v_bfi_b32 v151, v93, v151, s52
	v_max3_f32 v88, v88, v144, v145
	v_max3_f32 v88, v88, v146, v147
	v_max3_f32 v88, v88, v148, v149
	v_max3_f32 v88, v88, v150, v151
.LattnB_done:
	s_mov_b64 s[6:7], 0
.LBB0_430:
	s_and_b64 vcc, exec, s[6:7]
	s_cbranch_vccz .LBB0_432
	s_nop 8
	v_pk_mul_f32 v[144:145], v[64:65], s[30:31] op_sel_hi:[1,0]
	v_pk_mul_f32 v[146:147], v[66:67], s[30:31] op_sel_hi:[1,0]
	v_max3_f32 v64, v144, s52, v145
	v_max3_f32 v64, v64, v146, v147
	v_pk_mul_f32 v[148:149], v[68:69], s[30:31] op_sel_hi:[1,0]
	v_pk_mul_f32 v[150:151], v[70:71], s[30:31] op_sel_hi:[1,0]
	v_max3_f32 v64, v64, v148, v149
	v_max3_f32 v64, v64, v150, v151
	v_pk_mul_f32 v[80:81], v[72:73], s[30:31] op_sel_hi:[1,0]
	v_pk_mul_f32 v[82:83], v[74:75], s[30:31] op_sel_hi:[1,0]
	v_max3_f32 v64, v64, v80, v81
	v_max3_f32 v64, v64, v82, v83
	v_pk_mul_f32 v[84:85], v[76:77], s[30:31] op_sel_hi:[1,0]
	v_pk_mul_f32 v[86:87], v[78:79], s[30:31] op_sel_hi:[1,0]
	v_max3_f32 v64, v64, v84, v85
	v_max3_f32 v88, v64, v86, v87

; DI unsigned pk2(float lo, float hi) { f32x2 v = {lo, hi}; return __builtin_bit_cast(unsigned, __builtin_convertvector(v, bf16x2v)); }
; #define MFMA32(a, b, c) __builtin_amdgcn_mfma_f32_32x32x16_bf16((a), (b), (c), 0, 0, 0)
; DI void attn_phase(LAS unsigned char* lds, ArgsRef a, int l, int vcu, int G) {
;     ...
;                 auto pv_chunk = [&](auto JC) { constexpr int J = decltype(JC)::value;
;                     float ps = 0.f;
; #pragma unroll
;                     for (int i = 0; i < 8; ++i) { const float p = __builtin_amdgcn_exp2f(s[8 * J + i] - mnew); s[8 * J + i] = p; ps += p; }
;                     u32x4 pw; pw.x = pk2(s[8 * J + 0], s[8 * J + 1]); pw.y = pk2(s[8 * J + 2], s[8 * J + 3]); pw.z = pk2(s[8 * J + 4], s[8 * J + 5]); pw.w = pk2(s[8 * J + 6], s[8 * J + 7]);
;                     const bf16x8 pf = __builtin_bit_cast(bf16x8, pw);
;                     o0 = MFMA32(vf[0][J], pf, o0);
;                     o1 = MFMA32(vf[1][J], pf, o1);
;                     return ps; };
;                 float ps;
;                 if (!loc || cb == HALF) { ps = pv_chunk(std::integral_constant<int, 0>{}); ps += pv_chunk(std::integral_constant<int, 1>{}); }
;                 else ps = pv_chunk(std::integral_constant<int, HALF>{});
.LBB0_434:
	v_sub_f32_e32 v64, v80, v153
	v_sub_f32_e32 v65, v81, v153
	v_sub_f32_e32 v66, v82, v153
	v_sub_f32_e32 v67, v83, v153
	v_sub_f32_e32 v68, v84, v153
	v_sub_f32_e32 v69, v85, v153
	v_sub_f32_e32 v70, v86, v153
	v_sub_f32_e32 v71, v87, v153
	s_cmp_eq_u32 s38, 0
	v_exp_f32_e32 v211, v64
	v_exp_f32_e32 v209, v65
	v_exp_f32_e32 v207, v66
	v_exp_f32_e32 v163, v67
	v_exp_f32_e32 v161, v68
	v_exp_f32_e32 v159, v69
	v_exp_f32_e32 v157, v70
	v_exp_f32_e32 v155, v71
	s_cselect_b64 s[8:9], -1, 0
	s_and_b64 s[8:9], s[10:11], s[8:9]
	s_mov_b64 s[6:7], -1
	s_and_b64 vcc, exec, s[8:9]
	s_cbranch_vccz .LBB0_436
	v_add_f32_e32 v64, 0, v211
	v_add_f32_e32 v80, v209, v64
	v_add_f32_e32 v80, v207, v80
	v_add_f32_e32 v80, v163, v80
	v_add_f32_e32 v80, v161, v80
	v_add_f32_e32 v80, v159, v80
	v_cvt_pk_bf16_f32 v234, v211, v209
	v_cvt_pk_bf16_f32 v235, v207, v163
	v_cvt_pk_bf16_f32 v236, v161, v159
	v_cvt_pk_bf16_f32 v237, v157, v155
	v_add_f32_e32 v80, v157, v80
	v_add_f32_e32 v154, v155, v80
	v_mfma_f32_32x32x16_bf16 v[16:31], v[128:131], v[234:237], v[16:31]
	s_mov_b64 s[6:7], 0
	v_mfma_f32_32x32x16_bf16 v[0:15], v[132:135], v[234:237], v[0:15]

; DI void attn_phase(LAS unsigned char* lds, ArgsRef a, int l, int vcu, int G) {
;     ...
;                 lrun = lrun * alpha + ps;
.LBB0_438:
	v_fmac_f32_e32 v154, v246, v152
	v_mov_b32_e32 v246, v154

; #define G_STAGE_A(bufoff, p0, p1, koff) do { \
;         __builtin_amdgcn_global_load_lds((const unsigned*)(gbase + (size_t)(unsigned)((p0) + (koff) + voffA[0])), (LAS unsigned*)(lds + (bufoff) + ldsw), 16, 0, 0); \
;         __builtin_amdgcn_global_load_lds((const unsigned*)(gbase + (size_t)(unsigned)((p1) + (koff) + voffA[1])), (LAS unsigned*)(lds + (bufoff) + ldsw + 8192), 16, 0, 0); } while (0)
; #define G_STAGE_B(bufoff, p, koff) do { \
;         __builtin_amdgcn_global_load_lds((const unsigned*)(gbase + (size_t)(unsigned)((p) + (koff) + voffB[0])), (LAS unsigned*)(lds + (bufoff) + ldsw), 16, 0, 0); \
;         __builtin_amdgcn_global_load_lds((const unsigned*)(gbase + (size_t)(unsigned)((p) + (koff) + voffB[1])), (LAS unsigned*)(lds + (bufoff) + ldsw + 8192), 16, 0, 0); } while (0)
; #define G_WAIT_V(n) asm volatile("s_waitcnt vmcnt(" #n ")" ::: "memory")
; #define G_BAR __builtin_amdgcn_s_barrier()
; template <class Epi>
; DI void gemm_phase(LAS unsigned char* lds, const Sched& S, const Epi& E, const int K) {
;     ...
;     f32x4 acc[2][2][4][2];
; #pragma unroll
;     for (int a = 0; a < 2; ++a)
; #pragma unroll
;         for (int b = 0; b < 2; ++b)
; #pragma unroll
;             for (int m = 0; m < 4; ++m)
; #pragma unroll
;                 for (int n = 0; n < 2; ++n) acc[a][b][m][n] = (f32x4){0.f, 0.f, 0.f, 0.f};
;     bf16x8 At[4][2], B0[2][2], B1[2][2];
;     ...
;     G_STAGE_B(G_SB(0, 0), cur.b, 0u); G_STAGE_B(G_SB(0, 1), cur.b + hstepB, 0u); G_STAGE_A(G_SA(0, 0), cur.a0, cur.a1, 0u); G_STAGE_A(G_SA(0, 1), cur.a2, cur.a3, 0u);
;     if (wr == 1) G_BAR;
;     G_WAIT_V(2); G_BAR;
;     ...
;     G_STAGE_B(G_SB(0, 0), cur.b, 0u); G_STAGE_A(G_SA(0, 0), cur.a0, cur.a1, 0u); G_STAGE_B(G_SB(0, 1), cur.b + hstepB, 0u); G_STAGE_A(G_SA(0, 1), cur.a2, cur.a3, 0u);
;     if (wr == 1) G_BAR;
;     G_WAIT_V(4); G_BAR;
;     ...
;     G_STAGE_B(G_SB(1, 0), cur.b, kstepB); G_STAGE_A(G_SA(1, 0), cur.a0, cur.a1, kstepA); G_STAGE_B(G_SB(1, 1), cur.b + hstepB, kstepB);
;     G_WAIT_V(6); G_BAR;
;     ...
; #pragma unroll
;         for (int a = 0; a < 2; ++a)
; #pragma unroll
;             for (int b = 0; b < 2; ++b)
; #pragma unroll
;                 for (int m = 0; m < 4; ++m)
; #pragma unroll
;                     for (int n = 0; n < 2; ++n) acc[a][b][m][n] = (f32x4){0.f, 0.f, 0.f, 0.f};
;         cur = nxt; ++ui;
.LBB0_488:
	v_lshrrev_b32_e32 v10, 1, v1
	v_and_b32_e32 v10, 24, v10
	v_and_b32_e32 v9, 15, v1
	v_lshlrev_b32_e32 v11, 1, v10
	v_lshlrev_b32_e32 v1, 2, v1
	s_and_b32 s9, s6, 3
	v_lshl_or_b32 v147, s7, 6, v9
	v_lshl_or_b32 v9, v9, 6, v11
	s_lshl_b32 s7, s7, 13
	v_and_b32_e32 v1, 32, v1
	v_bitop3_b32 v11, v9, s7, v1 bitop3:0xde
	s_lshl_b32 s7, s9, 5
	s_lshl_b32 s10, s9, 12
	s_add_u32 s12, s82, 0x25c00000
	v_bitop3_b32 v148, v9, s10, v1 bitop3:0xde
	s_addc_u32 s13, s83, 0
	s_add_i32 s10, s40, 0x80
	v_add_u32_e32 v1, s10, v144
	s_add_i32 m0, s50, 0x18000
	s_waitcnt vmcnt(2)
	s_barrier
	global_load_lds_dwordx4 v1, s[82:83]
	v_add_u32_e32 v1, s10, v146
	s_add_i32 m0, s50, 0x1a000
	s_add_i32 s57, s50, 0x8000
	global_load_lds_dwordx4 v1, s[82:83]
	v_add_u32_e32 v1, 0x80, v8
	s_mov_b32 m0, s57
	s_add_i32 s58, s50, 0xa000
	global_load_lds_dwordx4 v1, s[82:83]
	v_add_u32_e32 v1, 0x80, v7
	s_mov_b32 m0, s58
	s_add_i32 s10, s40, 0x80080
	global_load_lds_dwordx4 v1, s[82:83]
	v_add_u32_e32 v1, s10, v144
	s_add_i32 m0, s50, 0x1c000
	v_and_b32_e32 v0, 1, v0
	global_load_lds_dwordx4 v1, s[82:83]
	v_add_u32_e32 v1, s10, v146
	s_add_i32 m0, s50, 0x1e000
	s_cmpk_lt_u32 s8, 0x100
	global_load_lds_dwordx4 v1, s[82:83]
	v_and_b32_e32 v1, 1, v4
	s_cselect_b64 s[14:15], -1, 0
	s_bfe_u32 s59, s6, 0x10001
	s_bfe_u32 s6, s9, 0x1a0001
	v_lshl_add_u32 v1, v1, 6, v6
	v_lshlrev_b32_e32 v4, 1, v5
	s_waitcnt vmcnt(6)
	v_or_b32_e32 v132, s7, v10
	v_bitop3_b32 v149, s7, 56, v10 bitop3:0xc8
	s_or_b32 s60, s6, 2
	v_readlane_b32 s6, v254, 39
	v_add3_u32 v150, v1, v4, s31
	v_lshl_add_u32 v0, v0, 6, v3
	v_lshlrev_b32_e32 v1, 1, v2
	v_lshlrev_b32_e32 v184, 1, v149
	v_readlane_b32 s7, v254, 40
	v_add3_u32 v151, v0, v1, s31
	v_mov_b32_e32 v0, 0
	v_lshl_add_u64 v[134:135], s[16:17], 0, v[184:185]
	v_lshl_add_u64 v[136:137], s[6:7], 0, v[184:185]
	s_mov_b32 s61, 0
	v_add_u32_e32 v152, 0, v11
	v_mov_b32_e32 v1, v0
	v_mov_b64_e32 v[2:3], 0
	v_mov_b64_e32 v[4:5], 0
	v_mov_b64_e32 v[6:7], 0
	v_mov_b64_e32 v[8:9], 0
	v_mov_b64_e32 v[10:11], 0
	v_mov_b64_e32 v[12:13], 0
	v_mov_b64_e32 v[14:15], 0
	v_mov_b64_e32 v[16:17], 0
	v_mov_b64_e32 v[18:19], 0
	v_mov_b64_e32 v[20:21], 0
	v_mov_b64_e32 v[22:23], 0
	v_mov_b64_e32 v[24:25], 0
	v_mov_b64_e32 v[26:27], 0
	v_mov_b64_e32 v[28:29], 0
	v_mov_b64_e32 v[30:31], 0
	v_mov_b64_e32 v[32:33], 0
	v_mov_b64_e32 v[34:35], 0
	v_mov_b64_e32 v[36:37], 0
	v_mov_b64_e32 v[38:39], 0
	v_mov_b64_e32 v[40:41], 0
	v_mov_b64_e32 v[42:43], 0
	v_mov_b64_e32 v[44:45], 0
	v_mov_b64_e32 v[46:47], 0
	v_mov_b64_e32 v[48:49], 0
	v_mov_b64_e32 v[50:51], 0
	v_mov_b64_e32 v[52:53], 0
	v_mov_b64_e32 v[54:55], 0
	v_mov_b64_e32 v[56:57], 0
	v_mov_b64_e32 v[58:59], 0
	v_mov_b64_e32 v[60:61], 0
	v_mov_b64_e32 v[62:63], 0
	v_mov_b64_e32 v[64:65], 0
	v_mov_b64_e32 v[66:67], 0
	v_mov_b64_e32 v[68:69], 0
	v_mov_b64_e32 v[70:71], 0
	v_mov_b64_e32 v[72:73], 0
	v_mov_b64_e32 v[74:75], 0
	v_mov_b64_e32 v[76:77], 0
	v_mov_b64_e32 v[78:79], 0
	v_mov_b64_e32 v[80:81], 0
	v_mov_b64_e32 v[82:83], 0
	v_mov_b64_e32 v[84:85], 0
	v_mov_b64_e32 v[86:87], 0
	v_mov_b64_e32 v[88:89], 0
	v_mov_b64_e32 v[90:91], 0
	v_mov_b64_e32 v[92:93], 0
	v_mov_b64_e32 v[94:95], 0
	v_mov_b64_e32 v[96:97], 0
	v_mov_b64_e32 v[98:99], 0
	v_mov_b64_e32 v[100:101], 0
	v_mov_b64_e32 v[102:103], 0
	v_mov_b64_e32 v[104:105], 0
	v_mov_b64_e32 v[106:107], 0
	v_mov_b64_e32 v[108:109], 0
	v_mov_b64_e32 v[110:111], 0
	v_mov_b64_e32 v[112:113], 0
	v_mov_b64_e32 v[114:115], 0
	v_mov_b64_e32 v[116:117], 0
	v_mov_b64_e32 v[118:119], 0
	v_mov_b64_e32 v[120:121], 0
	v_mov_b64_e32 v[122:123], 0
	v_mov_b64_e32 v[124:125], 0
	v_mov_b64_e32 v[126:127], 0
	s_barrier
	s_branch .LBB0_491
.LBB0_489:
	v_mov_b32_e32 v0, 0
	s_mov_b32 s38, s62
	s_mov_b32 s39, s63
	s_mov_b32 s40, s68
	s_mov_b32 s41, s70
	s_mov_b32 s44, s66
	s_mov_b32 s45, s67
	s_mov_b32 s46, s69
	s_mov_b32 s61, s71
	v_mov_b32_e32 v1, v0
	v_mov_b64_e32 v[2:3], 0
	v_mov_b64_e32 v[4:5], 0
	v_mov_b64_e32 v[6:7], 0
	v_mov_b64_e32 v[8:9], 0
	v_mov_b64_e32 v[10:11], 0
	v_mov_b64_e32 v[12:13], 0
	v_mov_b64_e32 v[14:15], 0
	v_mov_b64_e32 v[16:17], 0
	v_mov_b64_e32 v[18:19], 0
	v_mov_b64_e32 v[20:21], 0
	v_mov_b64_e32 v[22:23], 0
	v_mov_b64_e32 v[24:25], 0
	v_mov_b64_e32 v[26:27], 0
	v_mov_b64_e32 v[28:29], 0
	v_mov_b64_e32 v[30:31], 0
	v_mov_b64_e32 v[32:33], 0
	v_mov_b64_e32 v[34:35], 0
	v_mov_b64_e32 v[36:37], 0
	v_mov_b64_e32 v[38:39], 0
	v_mov_b64_e32 v[40:41], 0
	v_mov_b64_e32 v[42:43], 0
	v_mov_b64_e32 v[44:45], 0
	v_mov_b64_e32 v[46:47], 0
	v_mov_b64_e32 v[48:49], 0
	v_mov_b64_e32 v[50:51], 0
	v_mov_b64_e32 v[52:53], 0
	v_mov_b64_e32 v[54:55], 0
	v_mov_b64_e32 v[56:57], 0
	v_mov_b64_e32 v[58:59], 0
	v_mov_b64_e32 v[60:61], 0
	v_mov_b64_e32 v[62:63], 0
	v_mov_b64_e32 v[64:65], 0
	v_mov_b64_e32 v[66:67], 0
	v_mov_b64_e32 v[68:69], 0
	v_mov_b64_e32 v[70:71], 0
	v_mov_b64_e32 v[72:73], 0
	v_mov_b64_e32 v[74:75], 0
	v_mov_b64_e32 v[76:77], 0
	v_mov_b64_e32 v[78:79], 0
	v_mov_b64_e32 v[80:81], 0
	v_mov_b64_e32 v[82:83], 0
	v_mov_b64_e32 v[84:85], 0
	v_mov_b64_e32 v[86:87], 0
	v_mov_b64_e32 v[88:89], 0
	v_mov_b64_e32 v[90:91], 0
	v_mov_b64_e32 v[92:93], 0
	v_mov_b64_e32 v[94:95], 0
	v_mov_b64_e32 v[96:97], 0
	v_mov_b64_e32 v[98:99], 0
	v_mov_b64_e32 v[100:101], 0
	v_mov_b64_e32 v[102:103], 0
	v_mov_b64_e32 v[104:105], 0
	v_mov_b64_e32 v[106:107], 0
	v_mov_b64_e32 v[108:109], 0
	v_mov_b64_e32 v[110:111], 0
	v_mov_b64_e32 v[112:113], 0
	v_mov_b64_e32 v[114:115], 0
	v_mov_b64_e32 v[116:117], 0
	v_mov_b64_e32 v[118:119], 0
	v_mov_b64_e32 v[120:121], 0
	v_mov_b64_e32 v[122:123], 0
	v_mov_b64_e32 v[124:125], 0
	v_mov_b64_e32 v[126:127], 0
